# attention: 4-buffer K/V LDS ring fed by global_load_lds DMA, one barrier per half-trip, waves 4-7 staggered one barrier behind waves 0-3; plus nt x stores
# speedup vs baseline: 1.0166x; 1.0055x over previous
; __device__ __forceinline__ unsigned f2bf_rne(float f) { unsigned u = __builtin_bit_cast(unsigned, f); return (u + 0x7fffu + ((u >> 16) & 1u)) >> 16; }
; __device__ __forceinline__ int crow(int r, int hi) { return (r & 3) + 8 * (r >> 2) + 4 * hi; }
; template <typename TQ>
; __device__ __forceinline__ void attn_dense_body(const TQ* __restrict__ Qb, const bf16* __restrict__ Kh, const bf16* __restrict__ Vh,
;                                                 unsigned short* __restrict__ Ob, int seq, char* lds) {
;     ...
;   if (hi == 0) li_l[r32] = l_reg; asm volatile("s_waitcnt lgkmcnt(0)" ::: "memory");
;   float rli[16];
; #pragma unroll
;   for (int r = 0; r < 16; ++r) rli[r] = __builtin_amdgcn_rcpf(li_l[crow(r, hi)]);
;   __syncthreads();
;   unsigned short* Os = (unsigned short*)lds + wid * (32 * 136);
; #pragma unroll
;   for (int r = 0; r < 16; ++r) { const int orow = crow(r, hi);
; #pragma unroll
;     for (int d0 = 0; d0 < 4; ++d0) Os[orow * 136 + d0 * 32 + r32] = (unsigned short)f2bf_rne(o[d0][r] * rli[r]); }
.LBB0_70:
	s_or_b64 exec, exec, s[0:1]
	s_waitcnt lgkmcnt(0)
	v_add_u32_e32 v72, v184, v208
	ds_read_b128 v[64:67], v72
	ds_read_b128 v[68:71], v72 offset:32
	s_movk_i32 s2, 0x2200
	v_lshlrev_b32_e32 v81, 1, v179
	v_mul_u32_u24_e32 v82, 0x440, v182
	s_waitcnt lgkmcnt(1)
	v_rcp_f32_e32 v73, v64
	v_rcp_f32_e32 v74, v65
	v_rcp_f32_e32 v75, v66
	v_rcp_f32_e32 v76, v67
	s_waitcnt lgkmcnt(0)
	v_rcp_f32_e32 v77, v68
	ds_read_b128 v[64:67], v72 offset:64
	v_rcp_f32_e32 v78, v69
	v_rcp_f32_e32 v79, v70
	v_rcp_f32_e32 v80, v71
	ds_read_b128 v[68:71], v72 offset:96
	v_mul_lo_u32 v72, v183, s2
	v_add_u32_e32 v72, 0, v72
	v_mul_f32_e32 v0, v0, v73
	v_add3_u32 v81, v72, v81, v82
	v_bfe_u32 v82, v0, 16, 1
	v_add3_u32 v0, v0, v82, s26
	s_cmp_lt_u32 s5, 0x2000
	s_cbranch_scc0 .Latt_skipX
	s_barrier
.Latt_skipX:
	s_waitcnt lgkmcnt(0)
	s_barrier
	ds_write_b16_d16_hi v81, v0
	v_mul_f32_e32 v0, v48, v73
	v_bfe_u32 v48, v0, 16, 1
	v_add3_u32 v0, v0, v48, s26
	ds_write_b16_d16_hi v81, v0 offset:64
	v_mul_f32_e32 v0, v32, v73
	v_bfe_u32 v32, v0, 16, 1
	v_add3_u32 v0, v0, v32, s26
	ds_write_b16_d16_hi v81, v0 offset:128
	v_mul_f32_e32 v0, v16, v73
	v_bfe_u32 v16, v0, 16, 1
	v_add3_u32 v0, v0, v16, s26
	ds_write_b16_d16_hi v81, v0 offset:192
	v_mul_f32_e32 v0, v1, v74
	v_bfe_u32 v1, v0, 16, 1
	v_add3_u32 v0, v0, v1, s26
	ds_write_b16_d16_hi v81, v0 offset:272
	v_mul_f32_e32 v0, v49, v74
	v_bfe_u32 v1, v0, 16, 1
	v_add3_u32 v0, v0, v1, s26
	ds_write_b16_d16_hi v81, v0 offset:336
	v_mul_f32_e32 v0, v33, v74
	v_bfe_u32 v1, v0, 16, 1
	v_add3_u32 v0, v0, v1, s26
	ds_write_b16_d16_hi v81, v0 offset:400
	v_mul_f32_e32 v0, v17, v74
	v_bfe_u32 v1, v0, 16, 1
	v_add3_u32 v0, v0, v1, s26
	ds_write_b16_d16_hi v81, v0 offset:464
	v_mul_f32_e32 v0, v2, v75
	v_bfe_u32 v1, v0, 16, 1
	v_add3_u32 v0, v0, v1, s26
	ds_write_b16_d16_hi v81, v0 offset:544
	v_mul_f32_e32 v0, v50, v75
	v_bfe_u32 v1, v0, 16, 1
	v_add3_u32 v0, v0, v1, s26
	ds_write_b16_d16_hi v81, v0 offset:608
	v_mul_f32_e32 v0, v34, v75
	v_bfe_u32 v1, v0, 16, 1
	v_add3_u32 v0, v0, v1, s26
	ds_write_b16_d16_hi v81, v0 offset:672
	v_mul_f32_e32 v0, v18, v75
	v_bfe_u32 v1, v0, 16, 1
	v_add3_u32 v0, v0, v1, s26
	ds_write_b16_d16_hi v81, v0 offset:736
	v_mul_f32_e32 v0, v3, v76
	v_bfe_u32 v1, v0, 16, 1
	v_add3_u32 v0, v0, v1, s26
	ds_write_b16_d16_hi v81, v0 offset:816
	v_mul_f32_e32 v0, v51, v76
	v_bfe_u32 v1, v0, 16, 1
	v_add3_u32 v0, v0, v1, s26
	ds_write_b16_d16_hi v81, v0 offset:880
	v_mul_f32_e32 v0, v35, v76
	v_bfe_u32 v1, v0, 16, 1
	v_add3_u32 v0, v0, v1, s26
	ds_write_b16_d16_hi v81, v0 offset:944
	v_mul_f32_e32 v0, v19, v76
	v_bfe_u32 v1, v0, 16, 1
	v_add3_u32 v0, v0, v1, s26
	ds_write_b16_d16_hi v81, v0 offset:1008
	v_mul_f32_e32 v0, v4, v77
	v_bfe_u32 v1, v0, 16, 1
	v_add3_u32 v0, v0, v1, s26
	ds_write_b16_d16_hi v81, v0 offset:2176
	v_mul_f32_e32 v0, v52, v77
	v_bfe_u32 v1, v0, 16, 1
	v_add3_u32 v0, v0, v1, s26
	ds_write_b16_d16_hi v81, v0 offset:2240
	v_mul_f32_e32 v0, v36, v77
	v_bfe_u32 v1, v0, 16, 1
	v_add3_u32 v0, v0, v1, s26
	ds_write_b16_d16_hi v81, v0 offset:2304
	v_mul_f32_e32 v0, v20, v77
	v_bfe_u32 v1, v0, 16, 1
	v_add3_u32 v0, v0, v1, s26
	ds_write_b16_d16_hi v81, v0 offset:2368
	v_mul_f32_e32 v0, v5, v78
	v_bfe_u32 v1, v0, 16, 1
	v_add3_u32 v0, v0, v1, s26
	ds_write_b16_d16_hi v81, v0 offset:2448
	v_mul_f32_e32 v0, v53, v78
	v_bfe_u32 v1, v0, 16, 1
	v_add3_u32 v0, v0, v1, s26
	ds_write_b16_d16_hi v81, v0 offset:2512
	v_mul_f32_e32 v0, v37, v78
	v_bfe_u32 v1, v0, 16, 1
	v_add3_u32 v0, v0, v1, s26
	ds_write_b16_d16_hi v81, v0 offset:2576
	v_mul_f32_e32 v0, v21, v78
	v_bfe_u32 v1, v0, 16, 1
	v_add3_u32 v0, v0, v1, s26
	ds_write_b16_d16_hi v81, v0 offset:2640
	v_mul_f32_e32 v0, v6, v79
	v_bfe_u32 v1, v0, 16, 1
	v_add3_u32 v0, v0, v1, s26
	ds_write_b16_d16_hi v81, v0 offset:2720
	v_mul_f32_e32 v0, v54, v79
	v_bfe_u32 v1, v0, 16, 1
	v_add3_u32 v0, v0, v1, s26
	ds_write_b16_d16_hi v81, v0 offset:2784
	v_mul_f32_e32 v0, v38, v79
	v_bfe_u32 v1, v0, 16, 1
	v_add3_u32 v0, v0, v1, s26
	ds_write_b16_d16_hi v81, v0 offset:2848
	v_mul_f32_e32 v0, v22, v79
	v_bfe_u32 v1, v0, 16, 1
	v_add3_u32 v0, v0, v1, s26
	ds_write_b16_d16_hi v81, v0 offset:2912
	v_mul_f32_e32 v0, v7, v80
	v_bfe_u32 v1, v0, 16, 1
	v_add3_u32 v0, v0, v1, s26
	ds_write_b16_d16_hi v81, v0 offset:2992
	v_mul_f32_e32 v0, v55, v80
	v_bfe_u32 v1, v0, 16, 1
	v_add3_u32 v0, v0, v1, s26
	ds_write_b16_d16_hi v81, v0 offset:3056
	v_mul_f32_e32 v0, v39, v80
	v_bfe_u32 v1, v0, 16, 1
	v_rcp_f32_e32 v64, v64
	v_add3_u32 v0, v0, v1, s26
	ds_write_b16_d16_hi v81, v0 offset:3120
	v_mul_f32_e32 v0, v23, v80
	v_bfe_u32 v1, v0, 16, 1
	v_add3_u32 v0, v0, v1, s26
	ds_write_b16_d16_hi v81, v0 offset:3184
	v_mul_f32_e32 v0, v8, v64
	v_bfe_u32 v1, v0, 16, 1
	v_add3_u32 v0, v0, v1, s26
	ds_write_b16_d16_hi v81, v0 offset:4352
	v_mul_f32_e32 v0, v56, v64
	v_bfe_u32 v1, v0, 16, 1
	v_add3_u32 v0, v0, v1, s26
	ds_write_b16_d16_hi v81, v0 offset:4416
	v_mul_f32_e32 v0, v40, v64
	v_bfe_u32 v1, v0, 16, 1
	v_rcp_f32_e32 v65, v65
	v_add3_u32 v0, v0, v1, s26
	ds_write_b16_d16_hi v81, v0 offset:4480
	v_mul_f32_e32 v0, v24, v64
	v_bfe_u32 v1, v0, 16, 1
	v_add3_u32 v0, v0, v1, s26
	ds_write_b16_d16_hi v81, v0 offset:4544
	v_mul_f32_e32 v0, v9, v65
	v_bfe_u32 v1, v0, 16, 1
	v_add3_u32 v0, v0, v1, s26
	ds_write_b16_d16_hi v81, v0 offset:4624
	v_mul_f32_e32 v0, v57, v65
	v_bfe_u32 v1, v0, 16, 1
	v_add3_u32 v0, v0, v1, s26
	ds_write_b16_d16_hi v81, v0 offset:4688
; __device__ __forceinline__ unsigned f2bf_rne(float f) { unsigned u = __builtin_bit_cast(unsigned, f); return (u + 0x7fffu + ((u >> 16) & 1u)) >> 16; }
; __device__ __forceinline__ int crow(int r, int hi) { return (r & 3) + 8 * (r >> 2) + 4 * hi; }
; template <typename TQ>
; __device__ __forceinline__ void attn_dense_body(const TQ* __restrict__ Qb, const bf16* __restrict__ Kh, const bf16* __restrict__ Vh,
;                                                 unsigned short* __restrict__ Ob, int seq, char* lds) {
;     ...
;   for (int r = 0; r < 16; ++r) { const int orow = crow(r, hi);
; #pragma unroll
;     for (int d0 = 0; d0 < 4; ++d0) Os[orow * 136 + d0 * 32 + r32] = (unsigned short)f2bf_rne(o[d0][r] * rli[r]); }
;   asm volatile("s_waitcnt lgkmcnt(0)" ::: "memory");
;   unsigned short* Ow = Ob + (long)(wid * QBLK) * LDO;
; #pragma unroll
;   for (int i = 0; i < 8; ++i) { const int cidx = lane + 64 * i, row = cidx >> 4, seg = cidx & 15;
;     const u32x4 v = *reinterpret_cast<const u32x4*>(Os + row * 136 + seg * 8);
;     *reinterpret_cast<u32x4*>(Ow + (long)row * LDO + seg * 8) = v; }
	v_mul_f32_e32 v0, v41, v65
	v_bfe_u32 v1, v0, 16, 1
	v_rcp_f32_e32 v66, v66
	v_add3_u32 v0, v0, v1, s26
	ds_write_b16_d16_hi v81, v0 offset:4752
	v_mul_f32_e32 v0, v25, v65
	v_bfe_u32 v1, v0, 16, 1
	v_add3_u32 v0, v0, v1, s26
	ds_write_b16_d16_hi v81, v0 offset:4816
	v_mul_f32_e32 v0, v10, v66
	v_bfe_u32 v1, v0, 16, 1
	v_add3_u32 v0, v0, v1, s26
	ds_write_b16_d16_hi v81, v0 offset:4896
	v_mul_f32_e32 v0, v58, v66
	v_bfe_u32 v1, v0, 16, 1
	v_add3_u32 v0, v0, v1, s26
	ds_write_b16_d16_hi v81, v0 offset:4960
	v_mul_f32_e32 v0, v42, v66
	v_bfe_u32 v1, v0, 16, 1
	v_rcp_f32_e32 v67, v67
	v_add3_u32 v0, v0, v1, s26
	ds_write_b16_d16_hi v81, v0 offset:5024
	v_mul_f32_e32 v0, v26, v66
	v_bfe_u32 v1, v0, 16, 1
	v_add3_u32 v0, v0, v1, s26
	ds_write_b16_d16_hi v81, v0 offset:5088
	v_mul_f32_e32 v0, v11, v67
	v_bfe_u32 v1, v0, 16, 1
	v_add3_u32 v0, v0, v1, s26
	ds_write_b16_d16_hi v81, v0 offset:5168
	v_mul_f32_e32 v0, v59, v67
	v_bfe_u32 v1, v0, 16, 1
	v_add3_u32 v0, v0, v1, s26
	ds_write_b16_d16_hi v81, v0 offset:5232
	v_mul_f32_e32 v0, v43, v67
	v_bfe_u32 v1, v0, 16, 1
	v_rcp_f32_e32 v68, v68
	v_add3_u32 v0, v0, v1, s26
	ds_write_b16_d16_hi v81, v0 offset:5296
	v_mul_f32_e32 v0, v27, v67
	v_bfe_u32 v1, v0, 16, 1
	v_add3_u32 v0, v0, v1, s26
	ds_write_b16_d16_hi v81, v0 offset:5360
	v_mul_f32_e32 v0, v12, v68
	v_bfe_u32 v1, v0, 16, 1
	v_add3_u32 v0, v0, v1, s26
	ds_write_b16_d16_hi v81, v0 offset:6528
	v_mul_f32_e32 v0, v60, v68
	v_bfe_u32 v1, v0, 16, 1
	v_add3_u32 v0, v0, v1, s26
	ds_write_b16_d16_hi v81, v0 offset:6592
	v_mul_f32_e32 v0, v44, v68
	v_bfe_u32 v1, v0, 16, 1
	v_rcp_f32_e32 v69, v69
	v_add3_u32 v0, v0, v1, s26
	ds_write_b16_d16_hi v81, v0 offset:6656
	v_mul_f32_e32 v0, v28, v68
	v_bfe_u32 v1, v0, 16, 1
	v_add3_u32 v0, v0, v1, s26
	ds_write_b16_d16_hi v81, v0 offset:6720
	v_mul_f32_e32 v0, v13, v69
	v_bfe_u32 v1, v0, 16, 1
	v_add3_u32 v0, v0, v1, s26
	ds_write_b16_d16_hi v81, v0 offset:6800
	v_mul_f32_e32 v0, v61, v69
	v_bfe_u32 v1, v0, 16, 1
	v_add3_u32 v0, v0, v1, s26
	ds_write_b16_d16_hi v81, v0 offset:6864
	v_mul_f32_e32 v0, v45, v69
	v_bfe_u32 v1, v0, 16, 1
	v_rcp_f32_e32 v70, v70
	v_add3_u32 v0, v0, v1, s26
	ds_write_b16_d16_hi v81, v0 offset:6928
	v_mul_f32_e32 v0, v29, v69
	v_bfe_u32 v1, v0, 16, 1
	v_add3_u32 v0, v0, v1, s26
	ds_write_b16_d16_hi v81, v0 offset:6992
	v_mul_f32_e32 v0, v14, v70
	v_bfe_u32 v1, v0, 16, 1
	v_add3_u32 v0, v0, v1, s26
	ds_write_b16_d16_hi v81, v0 offset:7072
	v_mul_f32_e32 v0, v62, v70
	v_bfe_u32 v1, v0, 16, 1
	v_add3_u32 v0, v0, v1, s26
	ds_write_b16_d16_hi v81, v0 offset:7136
	v_mul_f32_e32 v0, v46, v70
	v_bfe_u32 v1, v0, 16, 1
	v_rcp_f32_e32 v71, v71
	v_add3_u32 v0, v0, v1, s26
	ds_write_b16_d16_hi v81, v0 offset:7200
	v_mul_f32_e32 v0, v30, v70
	v_bfe_u32 v1, v0, 16, 1
	v_add3_u32 v0, v0, v1, s26
	ds_write_b16_d16_hi v81, v0 offset:7264
	v_mul_f32_e32 v0, v15, v71
	v_bfe_u32 v1, v0, 16, 1
	v_add3_u32 v0, v0, v1, s26
	ds_write_b16_d16_hi v81, v0 offset:7344
	v_mul_f32_e32 v0, v63, v71
	v_bfe_u32 v1, v0, 16, 1
	v_add3_u32 v0, v0, v1, s26
	ds_write_b16_d16_hi v81, v0 offset:7408
	v_mul_f32_e32 v0, v47, v71
	v_bfe_u32 v1, v0, 16, 1
	v_add3_u32 v0, v0, v1, s26
	ds_write_b16_d16_hi v81, v0 offset:7472
	v_mul_f32_e32 v0, v31, v71
	v_readlane_b32 s0, v254, 39
	v_bfe_u32 v1, v0, 16, 1
	v_readlane_b32 s1, v254, 40
	s_add_u32 s0, s0, s40
	v_add3_u32 v0, v0, v1, s26
	v_ashrrev_i32_e32 v179, 31, v178
	s_addc_u32 s1, s1, s41
	ds_write_b16_d16_hi v81, v0 offset:7536
	v_lshlrev_b64 v[0:1], 11, v[178:179]
	v_lshrrev_b32_e32 v6, 4, v177
	v_lshl_add_u64 v[4:5], s[0:1], 0, v[0:1]
	v_lshlrev_b32_e32 v208, 1, v176
	v_mul_u32_u24_e32 v0, 0x110, v6
	s_waitcnt lgkmcnt(0)
	v_add3_u32 v12, v72, v208, v0
	ds_read_b128 v[0:3], v12
	v_lshl_add_u64 v[8:9], v[4:5], 0, v[208:209]
	v_lshlrev_b32_e32 v208, 11, v6
	ds_read_b128 v[4:7], v12 offset:1088
	v_lshl_add_u64 v[10:11], v[8:9], 0, v[208:209]
	s_waitcnt lgkmcnt(1)
	global_store_dwordx4 v[10:11], v[0:3], off
	s_mov_b32 s0, s86
	s_nop 0
	v_or_b32_e32 v0, 0x2000, v208
	v_mov_b32_e32 v1, v209
	v_lshl_add_u64 v[0:1], v[8:9], 0, v[0:1]
	s_waitcnt lgkmcnt(0)
	global_store_dwordx4 v[0:1], v[4:7], off
	ds_read_b128 v[0:3], v12 offset:2176
	s_nop 0
	v_or_b32_e32 v4, 0x4000, v208
	v_mov_b32_e32 v5, v209
	v_lshl_add_u64 v[10:11], v[8:9], 0, v[4:5]
	ds_read_b128 v[4:7], v12 offset:3264
	s_waitcnt lgkmcnt(1)
	global_store_dwordx4 v[10:11], v[0:3], off
	s_nop 1
	v_or_b32_e32 v0, 0x6000, v208
	v_mov_b32_e32 v1, v209
	v_lshl_add_u64 v[0:1], v[8:9], 0, v[0:1]
	s_waitcnt lgkmcnt(0)
	global_store_dwordx4 v[0:1], v[4:7], off
	ds_read_b128 v[0:3], v12 offset:4352
	s_nop 0
	v_or_b32_e32 v4, 0x8000, v208
	v_mov_b32_e32 v5, v209
	v_lshl_add_u64 v[10:11], v[8:9], 0, v[4:5]
	ds_read_b128 v[4:7], v12 offset:5440
	s_waitcnt lgkmcnt(1)
	global_store_dwordx4 v[10:11], v[0:3], off
	v_or_b32_e32 v10, 0xc000, v208
	v_mov_b32_e32 v11, v209
	v_or_b32_e32 v0, 0xa000, v208
	v_mov_b32_e32 v1, v209
	v_lshl_add_u64 v[0:1], v[8:9], 0, v[0:1]
	s_waitcnt lgkmcnt(0)
	global_store_dwordx4 v[0:1], v[4:7], off
	ds_read_b128 v[0:3], v12 offset:6528
	ds_read_b128 v[4:7], v12 offset:7616
	v_lshl_add_u64 v[10:11], v[8:9], 0, v[10:11]
	v_or_b32_e32 v208, 0xe000, v208
	s_waitcnt lgkmcnt(1)
	global_store_dwordx4 v[10:11], v[0:3], off
	s_nop 1
	v_lshl_add_u64 v[0:1], v[8:9], 0, v[208:209]
	s_waitcnt lgkmcnt(0)
	global_store_dwordx4 v[0:1], v[4:7], off
	s_barrier
	s_add_i32 s49, s0, s49
	s_cmp_ge_i32 s49, s48
	s_cbranch_scc1 .LBB0_68

; __device__ __forceinline__ int opaque_tid() { int t = (int)threadIdx.x; asm volatile("" : "+v"(t)); return t; }
; __device__ __forceinline__ int v_st(int k, int c) { const int kk = (k & ~0xC) | ((k & 4) << 1) | ((k & 8) >> 1); return ((kk >> 3) * 4 + (c >> 5)) * 512 + ((kk & 7) * 32 + (c & 31)) * 2; }
; __device__ __forceinline__ int v_rd_base(int lane) { return ((lane & 3) << 3) | (((lane >> 2) & 3) << 6) | (((lane >> 4) & 1) << 5) | (((lane >> 5) & 1) << 8); }
; #define SLOAD(i, k0) do { sr_[i].vs0 = St::ld8(&Vh[(long)((k0) + sr) * LDK + sc]); sr_[i].vs1 = St::ld8(&Vh[(long)((k0) + 32 + sr) * LDK + sc]); \
;     sr_[i].ks0 = St::ld8(&Kh[(long)((k0) + sr) * LDK + sc]); sr_[i].ks1 = St::ld8(&Kh[(long)((k0) + 32 + sr) * LDK + sc]); } while (0)
; #define SWAIT() do { if constexpr (SDEPTH == 2) asm volatile("s_waitcnt vmcnt(4)" ::: "memory"); else asm volatile("s_waitcnt vmcnt(0)" ::: "memory"); } while (0)
; template <typename TQ>
; __device__ __forceinline__ void attn_dense_body(const TQ* __restrict__ Qb, const bf16* __restrict__ Kh, const bf16* __restrict__ Vh,
;                                                 unsigned short* __restrict__ Ob, int seq, char* lds) {
;     ...
;   const int tid = ::opaque_tid(), wid = tid >> 6, lane = tid & 63, r32 = lane & 31, hi = lane >> 5;
;   bf16* V_lds = (bf16*)lds; bf16* K_lds = (bf16*)(lds + 2 * SHM_V);
;   float* ws = (float*)(lds + 2 * SHM_V + 2 * SHM_K) + wid * 64; float* li_l = ws; float* al_l = ws + 32;
;   float m_reg = -1e30f, l_reg = 0; f32x16 o[4] = {}; bf16x8 qr[8];
;   const TQ* Qw = Qb + (long)(wid * QBLK + r32) * LDQ + hi * 8;
; #pragma unroll
;   for (int d0 = 0; d0 < 8; ++d0) qr[d0] = SQ::tobf(SQ::ld8(Qw + d0 * 16));
;   const int sr = tid >> 4, sc = (tid & 15) * 8, vst0 = v_st(sr, sc), vst1 = v_st(32 + sr, sc);
;   const int vb0 = (int)(uintptr_t)V_lds + v_rd_base(lane);
;   struct { typename St::T vs0, vs1, ks0, ks1; } sr_[SDEPTH];
;     ...
;   f32x16 pA0, pA1, pB0, pB1; float mnA, mnB, alA, alB; bf16x8 pa0, pa1, pa2, pa3; const int NT = seq / KVBLK;
;   constexpr int SE = 0, SO = SDEPTH - 1;
;   SLOAD(SE, 0); asm volatile("s_waitcnt vmcnt(0)" ::: "memory"); SWRITE(0, SE); __syncthreads();
;   qkt(pA0, pA1, K_lds, qr, r32, hi); partialSM(pA0, pA1, m_reg, mnA, alA);
;   SLOAD(SO, KVBLK); if constexpr (SDEPTH == 2) { if (2 < NT) SLOAD(SE, 2 * KVBLK); }
;   SWAIT(); SWRITE(1, SO); __syncthreads();
.LBB0_75:
	s_lshl_b64 s[40:41], s[0:1], 1
	v_readlane_b32 s0, v254, 41
	v_readlane_b32 s1, v254, 42
	s_add_u32 s46, s0, s40
	v_mov_b32_e32 v74, v211
	s_addc_u32 s47, s1, s41
	s_lshl_b64 s[0:1], s[38:39], 1
	s_add_u32 s38, s58, s0
	v_ashrrev_i32_e32 v16, 4, v74
	v_lshlrev_b32_e32 v22, 3, v74
	v_add_u32_e32 v18, 32, v16
	s_addc_u32 s39, s59, s1
	v_and_b32_e32 v176, 0x78, v22
	v_ashrrev_i32_e32 v17, 31, v16
	v_ashrrev_i32_e32 v19, 31, v18
	s_add_u32 s42, s24, s0
	v_lshlrev_b32_e32 v23, 1, v176
	v_lshlrev_b64 v[48:49], 8, v[16:17]
	v_lshlrev_b64 v[8:9], 8, v[18:19]
	s_addc_u32 s43, s25, s1
	s_mov_b64 s[6:7], s[38:39]
	s_mov_b64 s[68:69], s[42:43]
	v_or_b32_e32 v50, v48, v23
	v_mov_b32_e32 v51, v49
	v_or_b32_e32 v8, v8, v23
	v_ashrrev_i32_e32 v183, 6, v74
	s_waitcnt lgkmcnt(0)
	v_lshl_add_u64 v[0:1], s[42:43], 0, v[50:51]
	v_lshl_add_u64 v[4:5], s[42:43], 0, v[8:9]
	v_lshl_add_u64 v[10:11], s[38:39], 0, v[50:51]
	v_lshl_add_u64 v[12:13], s[38:39], 0, v[8:9]
	v_and_b32_e32 v179, 31, v74
	v_lshlrev_b32_e32 v178, 5, v183
	global_load_dwordx4 v[0:3], v[0:1], off
	s_nop 0
	global_load_dwordx4 v[4:7], v[4:5], off
	s_nop 0
	global_load_dwordx4 v[8:11], v[10:11], off
	s_nop 0
	global_load_dwordx4 v[12:15], v[12:13], off
	v_or_b32_e32 v20, v178, v179
	v_ashrrev_i32_e32 v21, 31, v20
	v_bfe_u32 v182, v74, 5, 1
	v_lshlrev_b64 v[20:21], 11, v[20:21]
	v_lshl_add_u64 v[20:21], s[46:47], 0, v[20:21]
	v_lshlrev_b32_e32 v208, 4, v182
	v_lshl_add_u64 v[20:21], v[20:21], 0, v[208:209]
	global_load_dwordx4 v[112:115], v[20:21], off
	global_load_dwordx4 v[108:111], v[20:21], off offset:32
	global_load_dwordx4 v[120:123], v[20:21], off offset:64
	global_load_dwordx4 v[124:127], v[20:21], off offset:96
	global_load_dwordx4 v[116:119], v[20:21], off offset:128
	global_load_dwordx4 v[104:107], v[20:21], off offset:160
	global_load_dwordx4 v[100:103], v[20:21], off offset:192
	global_load_dwordx4 v[96:99], v[20:21], off offset:224
	v_and_b32_e32 v19, 0xfffff0, v16
	v_lshlrev_b32_e32 v24, 1, v16
	v_lshrrev_b32_e32 v25, 1, v16
	v_and_b32_e32 v26, 3, v16
	v_and_or_b32 v19, v24, 8, v19
	v_and_or_b32 v24, v25, 4, v26
	v_and_b32_e32 v25, 0xfffff0, v18
	v_lshlrev_b32_e32 v26, 1, v18
	v_and_b32_e32 v17, 0x70, v74
	v_bfe_u32 v22, v22, 5, 2
	v_lshlrev_b32_e32 v16, 8, v16
	v_lshlrev_b32_e32 v18, 8, v18
	v_lshrrev_b32_e32 v19, 1, v19
	v_and_or_b32 v25, v26, 8, v25
	v_lshlrev_b32_e32 v52, 4, v74
	v_bitop3_b32 v16, v23, v16, v17 bitop3:0xde
	v_bitop3_b32 v17, v23, v18, v17 bitop3:0xde
	v_or_b32_e32 v18, v19, v22
	v_lshrrev_b32_e32 v19, 1, v25
	v_lshlrev_b32_e32 v68, 8, v179
	v_and_b32_e32 v69, 0x70, v52
	v_lshlrev_b32_e32 v24, 6, v24
	v_and_b32_e32 v28, 48, v23
	v_add_u32_e32 v189, 0, v16
	v_add_u32_e32 v190, 0, v17
	v_lshlrev_b32_e32 v16, 9, v18
	v_or_b32_e32 v17, v19, v22
	v_bitop3_b32 v27, v208, v68, v69 bitop3:0xde
	v_or3_b32 v16, v16, v24, v28
	v_lshlrev_b32_e32 v17, 9, v17
	v_or3_b32 v17, v17, v24, v28
	v_add_u32_e32 v191, 0, v16
	v_add_u32_e32 v193, 0, v27
	s_waitcnt vmcnt(0)
	v_add_u32_e32 v192, 0, v17
	s_mov_b64 s[28:29], 0x4000
	s_add_i32 s3, 0, 0x20800
	v_and_b32_e32 v71, 0xc0, v52
	v_and_b32_e32 v177, 63, v74
	v_lshlrev_b32_e32 v70, 3, v177
	s_mov_b32 s4, 0x42b504f3
	s_cmp_lg_u32 0, -1
	s_mov_b32 s72, s73
	s_mov_b32 s74, s73
	s_mov_b32 s75, s73
	s_waitcnt vmcnt(0)
	ds_write_b128 v191, v[0:3]
	s_waitcnt vmcnt(10)
	ds_write_b128 v192, v[4:7]
	s_waitcnt vmcnt(9)
	ds_write_b128 v189, v[8:11] offset:32768
	s_waitcnt vmcnt(8)
	ds_write_b128 v190, v[12:15] offset:32768
	s_waitcnt lgkmcnt(0)
	s_barrier
	ds_read_b128 v[0:3], v193 offset:32768
	ds_read_b128 v[4:7], v193 offset:40960
	s_waitcnt vmcnt(7) lgkmcnt(1)
	v_mfma_f32_32x32x16_bf16 v[16:31], v[0:3], v[112:115], 0
	v_or_b32_e32 v0, 32, v208
	v_bitop3_b32 v0, v0, v68, v69 bitop3:0xde
	v_add_u32_e32 v198, 0, v0
	v_and_b32_e32 v12, 0x3fffffc0, v74
	v_lshl_add_u64 v[8:9], v[50:51], 0, s[28:29]
	s_mov_b64 s[28:29], 0x6000
	v_lshl_add_u64 v[10:11], v[50:51], 0, s[28:29]
	s_waitcnt lgkmcnt(0)
	v_mfma_f32_32x32x16_bf16 v[32:47], v[4:7], v[112:115], 0
	ds_read_b128 v[0:3], v198 offset:32768
	ds_read_b128 v[4:7], v198 offset:40960
	v_lshl_add_u32 v184, v12, 2, s3
	v_lshl_add_u64 v[12:13], s[42:43], 0, v[8:9]
	v_lshl_add_u64 v[14:15], s[42:43], 0, v[10:11]
	s_mov_b64 s[28:29], 0x8000
	s_cselect_b32 s3, 0, 0
	s_mov_b32 s76, s73
	s_waitcnt vmcnt(6) lgkmcnt(1)
	v_mfma_f32_32x32x16_bf16 v[16:31], v[0:3], v[108:111], v[16:31]
	v_or_b32_e32 v0, 64, v208
	v_bitop3_b32 v0, v0, v68, v69 bitop3:0xde
	v_add_u32_e32 v197, 0, v0
	s_mov_b32 s77, s73
	s_mov_b32 s78, s73
	s_mov_b32 s79, s73
	s_mov_b32 s80, s73
	s_waitcnt lgkmcnt(0)
	v_mfma_f32_32x32x16_bf16 v[32:47], v[4:7], v[108:111], v[32:47]
	ds_read_b128 v[0:3], v197 offset:32768
	ds_read_b128 v[4:7], v197 offset:40960
	s_mov_b32 s81, s73
	s_mov_b32 s82, s73
	s_mov_b32 s83, s73
	s_mov_b32 s84, s73
	s_mov_b32 s85, s73
	s_mov_b32 s86, s73
	s_waitcnt vmcnt(5) lgkmcnt(1)
	v_mfma_f32_32x32x16_bf16 v[16:31], v[0:3], v[120:123], v[16:31]
	v_or_b32_e32 v0, 0x60, v208
	v_bitop3_b32 v0, v0, v68, v69 bitop3:0xde
	v_add_u32_e32 v196, 0, v0
	s_mov_b32 s87, s73
	v_lshl_add_u32 v185, v179, 2, v184
	v_mov_b32_e32 v186, 0
	s_waitcnt lgkmcnt(0)
	v_mfma_f32_32x32x16_bf16 v[32:47], v[4:7], v[120:123], v[32:47]
	ds_read_b128 v[0:3], v196 offset:32768
	ds_read_b128 v[4:7], v196 offset:40960
	s_waitcnt vmcnt(4) lgkmcnt(1)
	v_mfma_f32_32x32x16_bf16 v[16:31], v[0:3], v[124:127], v[16:31]
	v_or_b32_e32 v0, 0x80, v208
	v_bitop3_b32 v0, v0, v68, v69 bitop3:0xde
	v_add_u32_e32 v194, 0, v0
	ds_read_b128 v[0:3], v194 offset:32768
	s_waitcnt lgkmcnt(1)
	v_mfma_f32_32x32x16_bf16 v[32:47], v[4:7], v[124:127], v[32:47]
	ds_read_b128 v[4:7], v194 offset:40960
	s_waitcnt vmcnt(3) lgkmcnt(1)
; #define SLOAD(i, k0) do { sr_[i].vs0 = St::ld8(&Vh[(long)((k0) + sr) * LDK + sc]); sr_[i].vs1 = St::ld8(&Vh[(long)((k0) + 32 + sr) * LDK + sc]); \
;     sr_[i].ks0 = St::ld8(&Kh[(long)((k0) + sr) * LDK + sc]); sr_[i].ks1 = St::ld8(&Kh[(long)((k0) + 32 + sr) * LDK + sc]); } while (0)
; #define SWAIT() do { if constexpr (SDEPTH == 2) asm volatile("s_waitcnt vmcnt(4)" ::: "memory"); else asm volatile("s_waitcnt vmcnt(0)" ::: "memory"); } while (0)
; __device__ __forceinline__ void partialSM(f32x16& p0, f32x16& p1, float& m_reg, float& mn, float& alpha) {
;   constexpr float C = SCALE * 1.4426950408889634f;
;   float pmax = p0[0]; for (int r = 1; r < 16; ++r) pmax = fmaxf(pmax, p0[r]); for (int r = 0; r < 16; ++r) pmax = fmaxf(pmax, p1[r]);
;   { auto rr = __builtin_amdgcn_permlane32_swap(__float_as_uint(pmax), __float_as_uint(pmax), false, false);
;     pmax = fmaxf(__uint_as_float(rr[0]), __uint_as_float(rr[1])); }
;   if (__builtin_expect(__all(pmax - m_reg <= THR / SCALE), 1)) { mn = m_reg; alpha = 1.f; }
;   else { mn = fmaxf(m_reg, pmax); alpha = __builtin_amdgcn_exp2f((m_reg - mn) * C); m_reg = mn; }
;   float mnC = -mn * C;
;   for (int r = 0; r < 16; ++r) p0[r] = fmaf(p0[r], C, mnC); for (int r = 0; r < 16; ++r) p1[r] = fmaf(p1[r], C, mnC);
;   for (int r = 0; r < 16; ++r) p0[r] = __builtin_amdgcn_exp2f(p0[r]);
; template <typename TQ>
; __device__ __forceinline__ void attn_dense_body(const TQ* __restrict__ Qb, const bf16* __restrict__ Kh, const bf16* __restrict__ Vh,
;                                                 unsigned short* __restrict__ Ob, int seq, char* lds) {
;     ...
;   SLOAD(SE, 0); asm volatile("s_waitcnt vmcnt(0)" ::: "memory"); SWRITE(0, SE); __syncthreads();
;   qkt(pA0, pA1, K_lds, qr, r32, hi); partialSM(pA0, pA1, m_reg, mnA, alA);
;   SLOAD(SO, KVBLK); if constexpr (SDEPTH == 2) { if (2 < NT) SLOAD(SE, 2 * KVBLK); }
;   SWAIT(); SWRITE(1, SO); __syncthreads();
	v_mfma_f32_32x32x16_bf16 v[16:31], v[0:3], v[116:119], v[16:31]
	v_or_b32_e32 v0, 0xa0, v208
	v_bitop3_b32 v0, v0, v68, v69 bitop3:0xde
	v_add_u32_e32 v195, 0, v0
	ds_read_b128 v[0:3], v195 offset:32768
	s_waitcnt lgkmcnt(1)
	v_mfma_f32_32x32x16_bf16 v[32:47], v[4:7], v[116:119], v[32:47]
	ds_read_b128 v[4:7], v195 offset:40960
	global_load_dwordx4 v[52:55], v[12:13], off
	global_load_dwordx4 v[56:59], v[14:15], off
	s_waitcnt vmcnt(4) lgkmcnt(1)
	v_mfma_f32_32x32x16_bf16 v[16:31], v[0:3], v[104:107], v[16:31]
	v_lshl_add_u64 v[0:1], s[38:39], 0, v[8:9]
	v_lshl_add_u64 v[2:3], s[38:39], 0, v[10:11]
	global_load_dwordx4 v[60:63], v[0:1], off
	global_load_dwordx4 v[64:67], v[2:3], off
	v_or_b32_e32 v0, 0xc0, v208
	v_bitop3_b32 v0, v0, v68, v69 bitop3:0xde
	v_add_u32_e32 v200, 0, v0
	ds_read_b128 v[0:3], v200 offset:32768
	v_lshlrev_b32_e32 v9, 1, v74
	v_and_or_b32 v8, v70, 24, v71
	s_waitcnt lgkmcnt(1)
	v_mfma_f32_32x32x16_bf16 v[32:47], v[4:7], v[104:107], v[32:47]
	v_and_b32_e32 v4, 32, v9
	v_and_b32_e32 v5, 0x100, v70
	v_or3_b32 v75, v8, v4, v5
	ds_read_b128 v[4:7], v200 offset:40960
	v_add_u32_e32 v188, s3, v75
	s_waitcnt vmcnt(5) lgkmcnt(1)
	v_mfma_f32_32x32x16_bf16 v[16:31], v[0:3], v[100:103], v[16:31]
	v_or_b32_e32 v0, 0xe0, v208
	v_bitop3_b32 v0, v0, v68, v69 bitop3:0xde
	v_add_u32_e32 v199, 0, v0
	ds_read_b128 v[0:3], v199 offset:32768
	ds_read_b128 v[68:71], v199 offset:40960
	s_waitcnt lgkmcnt(2)
	v_mfma_f32_32x32x16_bf16 v[32:47], v[4:7], v[100:103], v[32:47]
	s_waitcnt vmcnt(4) lgkmcnt(1)
	v_mfma_f32_32x32x16_bf16 v[16:31], v[0:3], v[96:99], v[16:31]
	v_mov_b64_e32 v[0:1], s[72:73]
	v_mov_b64_e32 v[14:15], s[86:87]
	v_mov_b64_e32 v[2:3], s[74:75]
	v_mov_b64_e32 v[4:5], s[76:77]
	v_mov_b64_e32 v[6:7], s[78:79]
	v_mov_b64_e32 v[8:9], s[80:81]
	v_mov_b64_e32 v[10:11], s[82:83]
	s_waitcnt lgkmcnt(0)
	v_mfma_f32_32x32x16_bf16 v[32:47], v[68:71], v[96:99], v[32:47]
	s_nop 2
	v_max_f32_e32 v68, v17, v17
	v_max_f32_e32 v69, v16, v16
	v_max_f32_e32 v68, v69, v68
	v_max3_f32 v68, v68, v18, v19
	v_max3_f32 v68, v68, v20, v21
	v_max3_f32 v68, v68, v22, v23
	v_max3_f32 v68, v68, v24, v25
	v_max3_f32 v68, v68, v26, v27
	v_max3_f32 v68, v68, v28, v29
	v_max3_f32 v68, v68, v30, v31
	v_max3_f32 v68, v68, v32, v33
	v_max3_f32 v68, v68, v34, v35
	v_max3_f32 v68, v68, v36, v37
	v_max3_f32 v68, v68, v38, v39
	v_max3_f32 v68, v68, v40, v41
	v_max3_f32 v68, v68, v42, v43
	v_max3_f32 v76, v68, v44, v45
	v_lshl_add_u64 v[68:69], v[50:51], 0, s[28:29]
	s_mov_b64 s[28:29], 0xa000
	v_lshl_add_u64 v[70:71], s[42:43], 0, v[68:69]
	v_lshl_add_u64 v[50:51], v[50:51], 0, s[28:29]
	v_lshl_add_u64 v[68:69], s[38:39], 0, v[68:69]
	v_lshl_add_u64 v[72:73], s[42:43], 0, v[50:51]
	global_load_dwordx4 v[128:131], v[70:71], off
	global_load_dwordx4 v[136:139], v[72:73], off
	v_lshl_add_u64 v[50:51], s[38:39], 0, v[50:51]
	global_load_dwordx4 v[132:135], v[68:69], off
	global_load_dwordx4 v[140:143], v[50:51], off
	v_max3_f32 v50, v76, v46, v47
	v_mov_b32_e32 v51, v50
	s_nop 1
	v_permlane32_swap_b32_e32 v50, v51
	v_max_f32_e32 v51, v51, v51
	v_max_f32_e32 v50, v50, v50
	v_max_f32_e32 v50, v50, v51
	v_add_f32_e32 v51, 0x7149f2ca, v50
	v_max_f32_e32 v50, 0xf149f2ca, v50
	v_cmp_ge_f32_e32 vcc, s4, v51
	v_sub_f32_e32 v51, 0xf149f2ca, v50
	v_mul_f32_e32 v51, 0x3e0293ee, v51
	v_exp_f32_e32 v51, v51
	s_cmp_eq_u64 vcc, exec
	s_cselect_b64 vcc, -1, 0
	s_addk_i32 s3, 0x4000
	v_cndmask_b32_e64 v201, v51, 1.0, vcc
	v_mov_b32_e32 v51, 0xf149f2ca
	v_cndmask_b32_e32 v168, v50, v51, vcc
	v_mul_f32_e32 v50, 0xbe0293ee, v168
	v_fmamk_f32 v16, v16, 0x3e0293ee, v50
	v_exp_f32_e32 v161, v16
	v_fmamk_f32 v16, v17, 0x3e0293ee, v50
	v_exp_f32_e32 v175, v16
	v_fmamk_f32 v16, v18, 0x3e0293ee, v50
	v_exp_f32_e32 v162, v16
	v_fmamk_f32 v16, v19, 0x3e0293ee, v50
	v_exp_f32_e32 v205, v16
	v_fmamk_f32 v16, v20, 0x3e0293ee, v50
	v_exp_f32_e32 v174, v16
	v_fmamk_f32 v16, v21, 0x3e0293ee, v50
	v_exp_f32_e32 v214, v16
	v_fmamk_f32 v16, v22, 0x3e0293ee, v50
	v_exp_f32_e32 v163, v16
	v_fmamk_f32 v16, v23, 0x3e0293ee, v50
	v_exp_f32_e32 v173, v16
	v_fmamk_f32 v16, v24, 0x3e0293ee, v50
	v_exp_f32_e32 v164, v16
	v_fmamk_f32 v16, v25, 0x3e0293ee, v50
	v_exp_f32_e32 v171, v16
	v_fmamk_f32 v16, v26, 0x3e0293ee, v50
	v_exp_f32_e32 v165, v16
	v_fmamk_f32 v16, v27, 0x3e0293ee, v50
	v_exp_f32_e32 v172, v16
	v_fmamk_f32 v16, v28, 0x3e0293ee, v50
	v_exp_f32_e32 v166, v16
	v_fmamk_f32 v16, v29, 0x3e0293ee, v50
	v_pk_fma_f32 v[144:145], v[46:47], s[22:23], v[50:51] op_sel_hi:[1,0,0]
	v_pk_fma_f32 v[150:151], v[44:45], s[22:23], v[50:51] op_sel_hi:[1,0,0]
	v_pk_fma_f32 v[154:155], v[42:43], s[22:23], v[50:51] op_sel_hi:[1,0,0]
	v_pk_fma_f32 v[146:147], v[40:41], s[22:23], v[50:51] op_sel_hi:[1,0,0]
	v_pk_fma_f32 v[148:149], v[38:39], s[22:23], v[50:51] op_sel_hi:[1,0,0]
	v_pk_fma_f32 v[152:153], v[36:37], s[22:23], v[50:51] op_sel_hi:[1,0,0]
	v_pk_fma_f32 v[156:157], v[34:35], s[22:23], v[50:51] op_sel_hi:[1,0,0]
	v_pk_fma_f32 v[158:159], v[32:33], s[22:23], v[50:51] op_sel_hi:[1,0,0]
	v_exp_f32_e32 v169, v16
	v_fmamk_f32 v16, v30, 0x3e0293ee, v50
	v_fmac_f32_e32 v50, 0x3e0293ee, v31
	v_add_u32_e32 v187, s3, v75
	v_readlane_b32 s3, v253, 29
	v_exp_f32_e32 v167, v16
	v_exp_f32_e32 v170, v50
	v_and_b32_e32 v16, 15, v74
	s_add_u32 s0, s3, s0
	v_readlane_b32 s3, v253, 30
	s_waitcnt vmcnt(4)
	v_lshl_or_b32 v48, v16, 4, v48
	s_addc_u32 s1, s3, s1
	v_mov_b64_e32 v[12:13], s[84:85]
	s_waitcnt vmcnt(7)
	ds_write_b128 v191, v[52:55] offset:16384
	s_waitcnt vmcnt(6)
	ds_write_b128 v192, v[56:59] offset:16384
	s_waitcnt vmcnt(5)
	ds_write_b128 v189, v[60:63] offset:49152
	s_waitcnt vmcnt(4)
	ds_write_b128 v190, v[64:67] offset:49152
	v_lshl_add_u64 v[180:181], s[0:1], 0, v[48:49]
	v_mov_b64_e32 v[62:63], v[14:15]
	v_mov_b64_e32 v[46:47], v[14:15]
	v_mov_b64_e32 v[30:31], v[14:15]
	v_readlane_b32 s84, v252, 4
	v_cmp_gt_u32_e64 s[38:39], 32, v177
	v_mov_b64_e32 v[60:61], v[12:13]
	v_mov_b64_e32 v[58:59], v[10:11]
	v_mov_b64_e32 v[56:57], v[8:9]
	v_mov_b64_e32 v[54:55], v[6:7]
	v_mov_b64_e32 v[52:53], v[4:5]
	v_mov_b64_e32 v[50:51], v[2:3]
	v_mov_b64_e32 v[48:49], v[0:1]
	v_mov_b64_e32 v[44:45], v[12:13]
	v_mov_b64_e32 v[42:43], v[10:11]
	v_mov_b64_e32 v[40:41], v[8:9]
	v_mov_b64_e32 v[38:39], v[6:7]
	v_mov_b64_e32 v[36:37], v[4:5]
	v_mov_b64_e32 v[34:35], v[2:3]
	v_mov_b64_e32 v[32:33], v[0:1]
	v_mov_b64_e32 v[28:29], v[12:13]
	v_mov_b64_e32 v[26:27], v[10:11]
	v_mov_b64_e32 v[24:25], v[8:9]
	v_mov_b64_e32 v[22:23], v[6:7]
	v_mov_b64_e32 v[20:21], v[4:5]
	v_mov_b64_e32 v[18:19], v[2:3]
	v_mov_b64_e32 v[16:17], v[0:1]
	v_readlane_b32 s85, v252, 5
	v_readlane_b32 s86, v252, 6
	s_mov_b32 s74, 0x7f800000
	s_mov_b32 s75, 0x2b000
	s_mov_b64 s[78:79], 0x800
	s_movk_i32 s77, 0x1ff
	s_waitcnt lgkmcnt(0)
	s_barrier
; #define SBAR() __builtin_amdgcn_sched_barrier(0)
; #define SLOAD(i, k0) do { sr_[i].vs0 = St::ld8(&Vh[(long)((k0) + sr) * LDK + sc]); sr_[i].vs1 = St::ld8(&Vh[(long)((k0) + 32 + sr) * LDK + sc]); \
;     sr_[i].ks0 = St::ld8(&Kh[(long)((k0) + sr) * LDK + sc]); sr_[i].ks1 = St::ld8(&Kh[(long)((k0) + 32 + sr) * LDK + sc]); } while (0)
; #define SWAIT() do { if constexpr (SDEPTH == 2) asm volatile("s_waitcnt vmcnt(4)" ::: "memory"); else asm volatile("s_waitcnt vmcnt(0)" ::: "memory"); } while (0)
; __device__ __forceinline__ void finishSM(f32x16& p0, f32x16& p1, float alpha, float& l_reg, bf16x8& pa0, bf16x8& pa1, bf16x8& pa2, bf16x8& pa3) {
;   for (int r = 0; r < 16; ++r) p1[r] = __builtin_amdgcn_exp2f(p1[r]);
;   float ps = 0; for (int r = 0; r < 16; ++r) ps += p0[r]; for (int r = 0; r < 16; ++r) ps += p1[r];
;   { auto rr = __builtin_amdgcn_permlane32_swap(__float_as_uint(ps), __float_as_uint(ps), false, false);
;     ps = __uint_as_float(rr[0]) + __uint_as_float(rr[1]); }
;   l_reg = l_reg * alpha + ps;
;     ...
;   PK4(p0, 0, pa0); PK4(p0, 8, pa1); PK4(p1, 0, pa2); PK4(p1, 8, pa3);
;     ...
; }
; __device__ __forceinline__ void qkt(f32x16& p0, f32x16& p1, const bf16* Ks, const bf16x8* qr, int r32, int hi) {
;   p0 = f32x16{}; p1 = f32x16{};
;   for (int d0 = 0; d0 < 8; ++d0) { int cb = (d0 * 16 + hi * 8) * 2;
;     bf16x8 b0 = *reinterpret_cast<const bf16x8*>((const char*)Ks + KSWZ(r32, cb));
;     bf16x8 b1 = *reinterpret_cast<const bf16x8*>((const char*)Ks + KSWZ(32 + r32, cb));
;     p0 = __builtin_amdgcn_mfma_f32_32x32x16_bf16(b0, qr[d0], p0, 0, 0, 0);
;     p1 = __builtin_amdgcn_mfma_f32_32x32x16_bf16(b1, qr[d0], p1, 0, 0, 0); }
; template <typename TQ>
; __device__ __forceinline__ void attn_dense_body(const TQ* __restrict__ Qb, const bf16* __restrict__ Kh, const bf16* __restrict__ Vh,
;                                                 unsigned short* __restrict__ Ob, int seq, char* lds) {
;     ...
;   SWAIT(); SWRITE(1, SO); __syncthreads();
;   for (int j = 1; j + 1 < NT; j += 2) {
;     SBAR(); qkt(pB0, pB1, (bf16*)((char*)K_lds + SHM_K), qr, r32, hi);
;     finishSM(pA0, pA1, alA, l_reg, pa0, pa1, pa2, pa3); SBAR();
;     SLOAD(SO, (j + SDEPTH) * KVBLK); SBAR();
	v_readlane_b32 s87, v252, 7
	s_waitcnt vmcnt(0)
	v_add_u32_e32 v136, 0x10000, v189
	v_add_u32_e32 v137, 0x10000, v190
	ds_write_b128 v136, v[132:135] offset:32768
	ds_write_b128 v137, v[140:143] offset:32768
	v_lshrrev_b32_e32 v138, 6, v211
	v_lshrrev_b32_e32 v139, 4, v246
	v_lshl_add_u32 v139, v138, 3, v139
	v_and_b32_e32 v129, 15, v246
	v_and_b32_e32 v128, 7, v139
	v_xor_b32_e32 v129, v129, v128
	v_lshlrev_b32_e32 v129, 4, v129
	v_lshl_add_u32 v128, v139, 8, v129
	v_xor_b32_e32 v129, 64, v129
	v_add_u32_e32 v139, 4, v139
	v_lshl_add_u32 v129, v139, 8, v129
	s_nop 1
	v_and_b32_e32 v136, 6, v138
	v_lshlrev_b32_e32 v136, 3, v136
	v_bfe_u32 v137, v246, 2, 2
	v_add_u32_e32 v136, v136, v137
	v_bfe_u32 v137, v246, 4, 1
	v_lshl_add_u32 v136, v137, 3, v136
	v_and_b32_e32 v137, 1, v138
	v_lshl_add_u32 v136, v137, 2, v136
	v_lshlrev_b32_e32 v136, 8, v136
	v_bfe_u32 v137, v246, 5, 1
	v_lshl_add_u32 v136, v137, 6, v136
	v_and_b32_e32 v137, 3, v246
	v_lshl_add_u32 v130, v137, 4, v136
	v_add_u32_e32 v131, 0x80, v130
	v_readfirstlane_b32 s5, v211
	s_nop 3
	s_lshr_b32 s5, s5, 6
	s_lshl_b32 s5, s5, 11
	s_mov_b32 s28, 0
	s_mov_b32 s29, 0x10000
	s_add_u32 s6, s6, 0xc000
	s_addc_u32 s7, s7, 0
	s_add_u32 s68, s68, 0x8000
	s_addc_u32 s69, s69, 0
	s_add_i32 m0, s5, 0x1c000
	s_nop 0
	global_load_lds_dwordx4 v128, s[6:7]
	s_add_i32 m0, s5, 0x1c400
	s_nop 0
	global_load_lds_dwordx4 v129, s[6:7]
	s_add_i32 m0, s5, 0x10000
	s_nop 0
	global_load_lds_dwordx4 v130, s[68:69]
	s_add_i32 m0, s5, 0x10400
	s_nop 0
	global_load_lds_dwordx4 v131, s[68:69]
	s_add_u32 s6, s6, 0x4000
	s_addc_u32 s7, s7, 0
	s_add_u32 s68, s68, 0x4000
	s_addc_u32 s69, s69, 0
	s_cmp_ge_u32 s5, 0x2000
	s_cbranch_scc0 .Latt_skipE0
	s_waitcnt lgkmcnt(0)
	s_barrier
.Latt_skipE0:
.LBB0_76:
	ds_read_b128 v[64:67], v193 offset:49152
	ds_read_b128 v[68:71], v193 offset:57344
	ds_read_b128 v[222:225], v198 offset:49152
	ds_read_b128 v[226:229], v198 offset:57344
	v_add_f32_e32 v160, 0, v161
	v_add_f32_e32 v160, v175, v160
	s_waitcnt lgkmcnt(3)
	v_mfma_f32_32x32x16_bf16 v[80:95], v[64:67], v[112:115], 0
	v_add_f32_e32 v160, v162, v160
	v_add_f32_e32 v160, v205, v160
	v_add_f32_e32 v160, v174, v160
	v_add_f32_e32 v160, v214, v160
	v_add_f32_e32 v160, v163, v160
	v_add_f32_e32 v160, v173, v160
	v_add_f32_e32 v160, v164, v160
	s_waitcnt lgkmcnt(2)
	v_mfma_f32_32x32x16_bf16 v[64:79], v[68:71], v[112:115], 0
	v_add_f32_e32 v160, v171, v160
	v_add_f32_e32 v160, v165, v160
	v_add_f32_e32 v160, v172, v160
	v_exp_f32_e32 v158, v158
	v_add_f32_e32 v160, v166, v160
	v_exp_f32_e32 v159, v159
	v_add_f32_e32 v160, v169, v160
	s_waitcnt lgkmcnt(1)
	v_mfma_f32_32x32x16_bf16 v[80:95], v[222:225], v[108:111], v[80:95]
	v_exp_f32_e32 v156, v156
	v_add_f32_e32 v160, v167, v160
	v_exp_f32_e32 v157, v157
	v_add_f32_e32 v160, v170, v160
	v_exp_f32_e32 v152, v152
	v_add_f32_e32 v160, v158, v160
	v_exp_f32_e32 v153, v153
	s_waitcnt lgkmcnt(0)
	v_mfma_f32_32x32x16_bf16 v[64:79], v[226:229], v[108:111], v[64:79]
	ds_read_b128 v[222:225], v197 offset:49152
	ds_read_b128 v[226:229], v197 offset:57344
	v_add_f32_e32 v160, v159, v160
	v_exp_f32_e32 v148, v148
	v_add_f32_e32 v160, v156, v160
	v_exp_f32_e32 v149, v149
	v_add_f32_e32 v160, v157, v160
	v_exp_f32_e32 v146, v146
	s_waitcnt lgkmcnt(1)
	v_mfma_f32_32x32x16_bf16 v[80:95], v[222:225], v[120:123], v[80:95]
	v_add_f32_e32 v160, v152, v160
	v_exp_f32_e32 v147, v147
	v_add_f32_e32 v160, v153, v160
	v_exp_f32_e32 v154, v154
	v_add_f32_e32 v160, v148, v160
	v_exp_f32_e32 v155, v155
	v_add_f32_e32 v160, v149, v160
	s_waitcnt lgkmcnt(0)
	v_mfma_f32_32x32x16_bf16 v[64:79], v[226:229], v[120:123], v[64:79]
	ds_read_b128 v[222:225], v196 offset:49152
	ds_read_b128 v[226:229], v196 offset:57344
	v_exp_f32_e32 v150, v150
	v_add_f32_e32 v160, v146, v160
	v_exp_f32_e32 v151, v151
	v_add_f32_e32 v160, v147, v160
	v_exp_f32_e32 v144, v144
	v_add_f32_e32 v160, v154, v160
	s_waitcnt lgkmcnt(1)
	v_mfma_f32_32x32x16_bf16 v[80:95], v[222:225], v[124:127], v[80:95]
	v_exp_f32_e32 v145, v145
	v_add_f32_e32 v160, v155, v160
	v_add_f32_e32 v160, v150, v160
	v_add_f32_e32 v160, v151, v160
	v_add_f32_e32 v160, v144, v160
	v_add_f32_e32 v202, v145, v160
	v_mov_b32_e32 v203, v202
	s_waitcnt lgkmcnt(0)
	v_mfma_f32_32x32x16_bf16 v[64:79], v[226:229], v[124:127], v[64:79]
	ds_read_b128 v[222:225], v194 offset:49152
	ds_read_b128 v[226:229], v194 offset:57344
	v_permlane32_swap_b32_e32 v202, v203
	s_waitcnt lgkmcnt(1)
	v_mfma_f32_32x32x16_bf16 v[80:95], v[222:225], v[116:119], v[80:95]
	s_waitcnt lgkmcnt(0)
	v_mfma_f32_32x32x16_bf16 v[64:79], v[226:229], v[116:119], v[64:79]
	ds_read_b128 v[222:225], v195 offset:49152
	ds_read_b128 v[226:229], v195 offset:57344
	s_waitcnt lgkmcnt(1)
	v_mfma_f32_32x32x16_bf16 v[80:95], v[222:225], v[104:107], v[80:95]
	s_waitcnt lgkmcnt(0)
	v_mfma_f32_32x32x16_bf16 v[64:79], v[226:229], v[104:107], v[64:79]
	ds_read_b128 v[222:225], v200 offset:49152
	ds_read_b128 v[226:229], v200 offset:57344
	s_waitcnt lgkmcnt(1)
	v_mfma_f32_32x32x16_bf16 v[80:95], v[222:225], v[100:103], v[80:95]
	s_waitcnt lgkmcnt(0)
	v_mfma_f32_32x32x16_bf16 v[64:79], v[226:229], v[100:103], v[64:79]
	ds_read_b128 v[222:225], v199 offset:49152
	ds_read_b128 v[226:229], v199 offset:57344
	v_cvt_pk_bf16_f32 v160, v161, v175
	v_cvt_pk_bf16_f32 v161, v162, v205
	v_cvt_pk_bf16_f32 v162, v174, v214
	v_cvt_pk_bf16_f32 v163, v163, v173
	v_cvt_pk_bf16_f32 v164, v164, v171
	v_cvt_pk_bf16_f32 v165, v165, v172
	s_waitcnt lgkmcnt(1)
	v_mfma_f32_32x32x16_bf16 v[80:95], v[222:225], v[96:99], v[80:95]
	v_cvt_pk_bf16_f32 v166, v166, v169
	v_cvt_pk_bf16_f32 v167, v167, v170
	v_cvt_pk_bf16_f32 v170, v158, v159
	v_cvt_pk_bf16_f32 v171, v156, v157
	v_cvt_pk_bf16_f32 v172, v152, v153
	v_cvt_pk_bf16_f32 v173, v148, v149
	v_cvt_pk_bf16_f32 v204, v146, v147
	s_waitcnt lgkmcnt(0)
; #define SBAR() __builtin_amdgcn_sched_barrier(0)
; #define SLOAD(i, k0) do { sr_[i].vs0 = St::ld8(&Vh[(long)((k0) + sr) * LDK + sc]); sr_[i].vs1 = St::ld8(&Vh[(long)((k0) + 32 + sr) * LDK + sc]); \
;     sr_[i].ks0 = St::ld8(&Kh[(long)((k0) + sr) * LDK + sc]); sr_[i].ks1 = St::ld8(&Kh[(long)((k0) + 32 + sr) * LDK + sc]); } while (0)
; #define SWAIT() do { if constexpr (SDEPTH == 2) asm volatile("s_waitcnt vmcnt(4)" ::: "memory"); else asm volatile("s_waitcnt vmcnt(0)" ::: "memory"); } while (0)
; template <int D0> __device__ __forceinline__ void pv_one(f32x16& od, int vb, bf16x8 pa0, bf16x8 pa1, bf16x8 pa2, bf16x8 pa3) {
;   const s16x4 l0 = tr_read<v_rd_off(D0, 0, 0)>(vb), h0 = tr_read<v_rd_off(D0, 0, 1)>(vb), l1 = tr_read<v_rd_off(D0, 1, 0)>(vb), h1 = tr_read<v_rd_off(D0, 1, 1)>(vb);
;   const s16x4 l2 = tr_read<v_rd_off(D0, 2, 0)>(vb), h2 = tr_read<v_rd_off(D0, 2, 1)>(vb), l3 = tr_read<v_rd_off(D0, 3, 0)>(vb), h3 = tr_read<v_rd_off(D0, 3, 1)>(vb);
;   asm volatile("s_waitcnt lgkmcnt(0)" ::: "memory"); SBAR();
;     ...
;   od = __builtin_amdgcn_mfma_f32_32x32x16_bf16(pa0, PK(l0, h0), od, 0, 0, 0);
;   od = __builtin_amdgcn_mfma_f32_32x32x16_bf16(pa1, PK(l1, h1), od, 0, 0, 0);
;   od = __builtin_amdgcn_mfma_f32_32x32x16_bf16(pa2, PK(l2, h2), od, 0, 0, 0);
;   od = __builtin_amdgcn_mfma_f32_32x32x16_bf16(pa3, PK(l3, h3), od, 0, 0, 0);
;     ...
; }
; __device__ __forceinline__ void pv_d0(f32x16* o, int vb, bf16x8 pa0, bf16x8 pa1, bf16x8 pa2, bf16x8 pa3) {
;   pv_one<0>(o[0], vb, pa0, pa1, pa2, pa3); pv_one<1>(o[1], vb, pa0, pa1, pa2, pa3); pv_one<2>(o[2], vb, pa0, pa1, pa2, pa3); pv_one<3>(o[3], vb, pa0, pa1, pa2, pa3);
; template <typename TQ>
; __device__ __forceinline__ void attn_dense_body(const TQ* __restrict__ Qb, const bf16* __restrict__ Kh, const bf16* __restrict__ Vh,
;                                                 unsigned short* __restrict__ Ob, int seq, char* lds) {
;     ...
;     finishSM(pA0, pA1, alA, l_reg, pa0, pa1, pa2, pa3); SBAR();
;     SLOAD(SO, (j + SDEPTH) * KVBLK); SBAR();
;     pv_d0(o, vb0, pa0, pa1, pa2, pa3); partialSM(pB0, pB1, m_reg, mnB, alB);
;     __syncthreads(); SWAIT(); SWRITE(0, SE);
;     RESC(alB); __syncthreads();
;     SBAR(); qkt(pA0, pA1, K_lds, qr, r32, hi);
	v_mfma_f32_32x32x16_bf16 v[64:79], v[226:229], v[96:99], v[64:79]
	v_cvt_pk_bf16_f32 v205, v154, v155
	v_cvt_pk_bf16_f32 v206, v150, v151
	v_permlane32_swap_b32_e32 v160, v162
	v_cvt_pk_bf16_f32 v207, v144, v145
	v_permlane32_swap_b32_e32 v204, v206
	v_permlane32_swap_b32_e32 v161, v163
	v_permlane32_swap_b32_e32 v164, v166
	v_permlane32_swap_b32_e32 v165, v167
	v_permlane32_swap_b32_e32 v170, v172
	v_permlane32_swap_b32_e32 v171, v173
	v_permlane32_swap_b32_e32 v205, v207
	ds_read_b64_tr_b16 v[222:223], v188 offset:0
	ds_read_b64_tr_b16 v[224:225], v188 offset:0x800
	ds_read_b64_tr_b16 v[226:227], v188 offset:0x1000
	ds_read_b64_tr_b16 v[228:229], v188 offset:0x1800
	ds_read_b64_tr_b16 v[230:231], v188 offset:0x2000
	ds_read_b64_tr_b16 v[232:233], v188 offset:0x2800
	ds_read_b64_tr_b16 v[234:235], v188 offset:0x3000
	ds_read_b64_tr_b16 v[236:237], v188 offset:0x3800
	s_waitcnt lgkmcnt(0)
	s_nop 0
	v_mfma_f32_32x32x16_bf16 v[0:15], v[160:163], v[222:225], v[0:15]
	ds_read_b64_tr_b16 v[222:223], v188 offset:0x200
	ds_read_b64_tr_b16 v[224:225], v188 offset:0xa00
	v_mfma_f32_32x32x16_bf16 v[0:15], v[164:167], v[226:229], v[0:15]
	ds_read_b64_tr_b16 v[226:227], v188 offset:0x1200
	ds_read_b64_tr_b16 v[228:229], v188 offset:0x1a00
	v_mfma_f32_32x32x16_bf16 v[0:15], v[170:173], v[230:233], v[0:15]
	ds_read_b64_tr_b16 v[230:231], v188 offset:0x2200
	ds_read_b64_tr_b16 v[232:233], v188 offset:0x2a00
	v_mfma_f32_32x32x16_bf16 v[0:15], v[204:207], v[234:237], v[0:15]
	ds_read_b64_tr_b16 v[234:235], v188 offset:0x3200
	ds_read_b64_tr_b16 v[236:237], v188 offset:0x3a00
	s_waitcnt lgkmcnt(0)
	v_mfma_f32_32x32x16_bf16 v[48:63], v[160:163], v[222:225], v[48:63]
	ds_read_b64_tr_b16 v[222:223], v188 offset:0x400
	ds_read_b64_tr_b16 v[224:225], v188 offset:0xc00
	v_mfma_f32_32x32x16_bf16 v[48:63], v[164:167], v[226:229], v[48:63]
	ds_read_b64_tr_b16 v[226:227], v188 offset:0x1400
	ds_read_b64_tr_b16 v[228:229], v188 offset:0x1c00
	v_mfma_f32_32x32x16_bf16 v[48:63], v[170:173], v[230:233], v[48:63]
	ds_read_b64_tr_b16 v[230:231], v188 offset:0x2400
	ds_read_b64_tr_b16 v[232:233], v188 offset:0x2c00
	v_mfma_f32_32x32x16_bf16 v[48:63], v[204:207], v[234:237], v[48:63]
	ds_read_b64_tr_b16 v[234:235], v188 offset:0x3400
	ds_read_b64_tr_b16 v[236:237], v188 offset:0x3c00
	s_waitcnt lgkmcnt(0)
	v_mfma_f32_32x32x16_bf16 v[32:47], v[160:163], v[222:225], v[32:47]
	ds_read_b64_tr_b16 v[222:223], v188 offset:0x600
	ds_read_b64_tr_b16 v[224:225], v188 offset:0xe00
	v_mfma_f32_32x32x16_bf16 v[32:47], v[164:167], v[226:229], v[32:47]
	ds_read_b64_tr_b16 v[226:227], v188 offset:0x1600
	ds_read_b64_tr_b16 v[228:229], v188 offset:0x1e00
	v_mfma_f32_32x32x16_bf16 v[32:47], v[170:173], v[230:233], v[32:47]
	ds_read_b64_tr_b16 v[230:231], v188 offset:0x2600
	ds_read_b64_tr_b16 v[232:233], v188 offset:0x2e00
	v_mfma_f32_32x32x16_bf16 v[32:47], v[204:207], v[234:237], v[32:47]
	ds_read_b64_tr_b16 v[234:235], v188 offset:0x3600
	ds_read_b64_tr_b16 v[236:237], v188 offset:0x3e00
	s_waitcnt lgkmcnt(0)
	v_mfma_f32_32x32x16_bf16 v[16:31], v[160:163], v[222:225], v[16:31]
	v_max_f32_e32 v160, v81, v81
	v_max_f32_e32 v161, v80, v80
	v_max_f32_e32 v160, v161, v160
	v_max3_f32 v160, v160, v82, v83
	v_max3_f32 v160, v160, v84, v85
	v_max3_f32 v160, v160, v86, v87
	v_max3_f32 v160, v160, v88, v89
	v_max3_f32 v160, v160, v90, v91
	v_max3_f32 v160, v160, v92, v93
	v_mfma_f32_32x32x16_bf16 v[16:31], v[164:167], v[226:229], v[16:31]
	v_max3_f32 v160, v160, v94, v95
	v_max3_f32 v160, v160, v64, v65
	v_max3_f32 v160, v160, v66, v67
	v_max3_f32 v160, v160, v68, v69
	v_max3_f32 v160, v160, v70, v71
	v_max3_f32 v160, v160, v72, v73
	v_max3_f32 v160, v160, v74, v75
	v_max3_f32 v160, v160, v76, v77
	v_mfma_f32_32x32x16_bf16 v[16:31], v[170:173], v[230:233], v[16:31]
	v_max3_f32 v160, v160, v78, v79
	v_mov_b32_e32 v161, v160
	s_nop 1
	v_permlane32_swap_b32_e32 v160, v161
	v_max_f32_e32 v161, v161, v161
	v_max_f32_e32 v160, v160, v160
	v_max_f32_e32 v160, v160, v161
	v_sub_f32_e32 v161, v160, v168
	v_cmp_ge_f32_e32 vcc, s4, v161
	v_max_f32_e32 v161, v168, v168
	v_max_f32_e32 v160, v161, v160
	v_mfma_f32_32x32x16_bf16 v[16:31], v[204:207], v[234:237], v[16:31]
	v_sub_f32_e32 v161, v168, v160
	v_mul_f32_e32 v161, 0x3e0293ee, v161
	v_exp_f32_e32 v161, v161
	s_cmp_eq_u64 vcc, exec
	s_cselect_b64 s[0:1], -1, 0
	s_waitcnt vmcnt(0)
	s_barrier
	v_cndmask_b32_e64 v204, v161, 1.0, s[0:1]
	v_cmp_gt_f32_e32 vcc, 1.0, v204
	s_add_i32 m0, s5, s28
	s_add_i32 m0, m0, 0x8000
	s_nop 0
	global_load_lds_dwordx4 v128, s[6:7]
	s_add_i32 m0, s5, s28
	s_add_i32 m0, m0, 0x8400
	s_nop 0
	global_load_lds_dwordx4 v129, s[6:7]
	s_add_i32 m0, s5, s29
	s_add_i32 m0, m0, 0x4000
	s_nop 0
	global_load_lds_dwordx4 v130, s[68:69]
	s_add_i32 m0, s5, s29
	s_add_i32 m0, m0, 0x4400
	s_nop 0
	global_load_lds_dwordx4 v131, s[68:69]
	s_add_u32 s6, s6, 0x4000
	s_addc_u32 s7, s7, 0
	s_add_u32 s68, s68, 0x4000
	s_addc_u32 s69, s69, 0
	v_xor_b32_e32 v193, 0x10000, v193
	v_xor_b32_e32 v194, 0x10000, v194
	v_xor_b32_e32 v195, 0x10000, v195
	v_xor_b32_e32 v196, 0x10000, v196
	v_xor_b32_e32 v197, 0x10000, v197
	v_xor_b32_e32 v198, 0x10000, v198
	v_xor_b32_e32 v199, 0x10000, v199
	v_xor_b32_e32 v200, 0x10000, v200
	s_cbranch_vccz .LBB0_80
; __device__ __forceinline__ void partialSM(f32x16& p0, f32x16& p1, float& m_reg, float& mn, float& alpha) {
;   constexpr float C = SCALE * 1.4426950408889634f;
;   float pmax = p0[0]; for (int r = 1; r < 16; ++r) pmax = fmaxf(pmax, p0[r]); for (int r = 0; r < 16; ++r) pmax = fmaxf(pmax, p1[r]);
;   { auto rr = __builtin_amdgcn_permlane32_swap(__float_as_uint(pmax), __float_as_uint(pmax), false, false);
;     pmax = fmaxf(__uint_as_float(rr[0]), __uint_as_float(rr[1])); }
;   if (__builtin_expect(__all(pmax - m_reg <= THR / SCALE), 1)) { mn = m_reg; alpha = 1.f; }
;   else { mn = fmaxf(m_reg, pmax); alpha = __builtin_amdgcn_exp2f((m_reg - mn) * C); m_reg = mn; }
;   float mnC = -mn * C;
;   for (int r = 0; r < 16; ++r) p0[r] = fmaf(p0[r], C, mnC); for (int r = 0; r < 16; ++r) p1[r] = fmaf(p1[r], C, mnC);
;   for (int r = 0; r < 16; ++r) p0[r] = __builtin_amdgcn_exp2f(p0[r]);
; }
; __device__ __forceinline__ void finishSM(f32x16& p0, f32x16& p1, float alpha, float& l_reg, bf16x8& pa0, bf16x8& pa1, bf16x8& pa2, bf16x8& pa3) {
;   for (int r = 0; r < 16; ++r) p1[r] = __builtin_amdgcn_exp2f(p1[r]);
;   float ps = 0; for (int r = 0; r < 16; ++r) ps += p0[r]; for (int r = 0; r < 16; ++r) ps += p1[r];
;   { auto rr = __builtin_amdgcn_permlane32_swap(__float_as_uint(ps), __float_as_uint(ps), false, false);
;     ps = __uint_as_float(rr[0]) + __uint_as_float(rr[1]); }
;   l_reg = l_reg * alpha + ps;
;     ...
;   PK4(p0, 0, pa0); PK4(p0, 8, pa1); PK4(p1, 0, pa2); PK4(p1, 8, pa3);
;     ...
; }
; __device__ __forceinline__ void qkt(f32x16& p0, f32x16& p1, const bf16* Ks, const bf16x8* qr, int r32, int hi) {
;   p0 = f32x16{}; p1 = f32x16{};
;   for (int d0 = 0; d0 < 8; ++d0) { int cb = (d0 * 16 + hi * 8) * 2;
;     bf16x8 b0 = *reinterpret_cast<const bf16x8*>((const char*)Ks + KSWZ(r32, cb));
;     bf16x8 b1 = *reinterpret_cast<const bf16x8*>((const char*)Ks + KSWZ(32 + r32, cb));
; template <typename TQ>
; __device__ __forceinline__ void attn_dense_body(const TQ* __restrict__ Qb, const bf16* __restrict__ Kh, const bf16* __restrict__ Vh,
;                                                 unsigned short* __restrict__ Ob, int seq, char* lds) {
;     ...
;     RESC(alB); __syncthreads();
;     SBAR(); qkt(pA0, pA1, K_lds, qr, r32, hi);
;     finishSM(pB0, pB1, alB, l_reg, pa0, pa1, pa2, pa3); SBAR();
;     if (SDEPTH == 1 || j + 3 < NT) SLOAD(SE, (j + 1 + SDEPTH) * KVBLK); SBAR();
	s_and_saveexec_b64 s[42:43], s[38:39]
	ds_write_b32 v185, v204 offset:128
	s_or_b64 exec, exec, s[42:43]
	s_waitcnt lgkmcnt(0)
	v_add_u32_e32 v161, v184, v208
	ds_read_b128 v[162:165], v161 offset:224
	ds_read_b128 v[170:173], v161 offset:192
	ds_read_b128 v[222:225], v161 offset:160
	ds_read_b128 v[226:229], v161 offset:128
	s_waitcnt lgkmcnt(3)
	v_pk_mul_f32 v[12:13], v[12:13], v[162:163]
	s_waitcnt lgkmcnt(2)
	v_pk_mul_f32 v[8:9], v[8:9], v[170:171]
	s_waitcnt lgkmcnt(1)
	v_pk_mul_f32 v[4:5], v[4:5], v[222:223]
	v_pk_mul_f32 v[14:15], v[14:15], v[164:165]
	v_pk_mul_f32 v[10:11], v[10:11], v[172:173]
	v_pk_mul_f32 v[6:7], v[6:7], v[224:225]
	s_waitcnt lgkmcnt(0)
	v_pk_mul_f32 v[2:3], v[2:3], v[228:229]
	v_pk_mul_f32 v[0:1], v[0:1], v[226:227]
	v_pk_mul_f32 v[60:61], v[60:61], v[162:163]
	v_pk_mul_f32 v[56:57], v[56:57], v[170:171]
	v_pk_mul_f32 v[52:53], v[52:53], v[222:223]
	v_pk_mul_f32 v[62:63], v[62:63], v[164:165]
	v_pk_mul_f32 v[58:59], v[58:59], v[172:173]
	v_pk_mul_f32 v[54:55], v[54:55], v[224:225]
	v_pk_mul_f32 v[50:51], v[50:51], v[228:229]
	v_pk_mul_f32 v[48:49], v[48:49], v[226:227]
	v_pk_mul_f32 v[44:45], v[44:45], v[162:163]
	v_pk_mul_f32 v[40:41], v[40:41], v[170:171]
	v_pk_mul_f32 v[36:37], v[36:37], v[222:223]
	v_pk_mul_f32 v[46:47], v[46:47], v[164:165]
	v_pk_mul_f32 v[42:43], v[42:43], v[172:173]
	v_pk_mul_f32 v[38:39], v[38:39], v[224:225]
	v_pk_mul_f32 v[34:35], v[34:35], v[228:229]
	v_pk_mul_f32 v[32:33], v[32:33], v[226:227]
	v_pk_mul_f32 v[28:29], v[28:29], v[162:163]
	v_pk_mul_f32 v[24:25], v[24:25], v[170:171]
	v_pk_mul_f32 v[20:21], v[20:21], v[222:223]
	v_pk_mul_f32 v[30:31], v[30:31], v[164:165]
	v_pk_mul_f32 v[26:27], v[26:27], v[172:173]
	v_pk_mul_f32 v[22:23], v[22:23], v[224:225]
	v_pk_mul_f32 v[18:19], v[18:19], v[228:229]
	v_pk_mul_f32 v[16:17], v[16:17], v[226:227]
.LBB0_80:
	v_cndmask_b32_e64 v205, v160, v168, s[0:1]
	v_mul_f32_e32 v206, 0xbe0293ee, v205
	v_fmamk_f32 v80, v80, 0x3e0293ee, v206
	v_fmamk_f32 v81, v81, 0x3e0293ee, v206
	v_fmamk_f32 v82, v82, 0x3e0293ee, v206
	v_fmamk_f32 v83, v83, 0x3e0293ee, v206
	v_fmamk_f32 v84, v84, 0x3e0293ee, v206
	v_fmamk_f32 v85, v85, 0x3e0293ee, v206
	v_fmamk_f32 v86, v86, 0x3e0293ee, v206
	v_fmamk_f32 v87, v87, 0x3e0293ee, v206
	v_fmamk_f32 v88, v88, 0x3e0293ee, v206
	v_fmamk_f32 v89, v89, 0x3e0293ee, v206
	v_fmamk_f32 v90, v90, 0x3e0293ee, v206
	v_fmamk_f32 v91, v91, 0x3e0293ee, v206
	v_fmamk_f32 v92, v92, 0x3e0293ee, v206
	v_fmamk_f32 v93, v93, 0x3e0293ee, v206
	v_fmamk_f32 v94, v94, 0x3e0293ee, v206
	v_fmamk_f32 v95, v95, 0x3e0293ee, v206
	v_exp_f32_e32 v160, v80
	v_exp_f32_e32 v175, v81
	v_exp_f32_e32 v161, v82
	v_exp_f32_e32 v174, v83
	v_exp_f32_e32 v162, v84
	v_exp_f32_e32 v173, v85
	v_exp_f32_e32 v163, v86
	v_exp_f32_e32 v172, v87
	v_exp_f32_e32 v164, v88
	v_exp_f32_e32 v171, v89
	v_exp_f32_e32 v165, v90
	v_exp_f32_e32 v170, v91
	v_exp_f32_e32 v166, v92
	v_exp_f32_e32 v169, v93
	v_exp_f32_e32 v167, v94
	v_exp_f32_e32 v168, v95
	v_fmamk_f32 v227, v64, 0x3e0293ee, v206
	v_fmamk_f32 v228, v65, 0x3e0293ee, v206
	v_fmamk_f32 v229, v66, 0x3e0293ee, v206
	v_fmamk_f32 v230, v67, 0x3e0293ee, v206
	v_fmamk_f32 v231, v68, 0x3e0293ee, v206
	v_fmamk_f32 v214, v69, 0x3e0293ee, v206
	v_fmamk_f32 v215, v70, 0x3e0293ee, v206
	v_fmamk_f32 v222, v71, 0x3e0293ee, v206
	v_fmamk_f32 v223, v72, 0x3e0293ee, v206
	v_fmamk_f32 v224, v73, 0x3e0293ee, v206
	v_fmamk_f32 v225, v74, 0x3e0293ee, v206
	v_fmamk_f32 v226, v75, 0x3e0293ee, v206
	v_fmamk_f32 v207, v76, 0x3e0293ee, v206
	v_fmamk_f32 v232, v77, 0x3e0293ee, v206
	v_fmamk_f32 v233, v78, 0x3e0293ee, v206
	v_fmac_f32_e32 v206, 0x3e0293ee, v79
	s_waitcnt lgkmcnt(0)
	ds_read_b128 v[64:67], v193 offset:32768
	ds_read_b128 v[68:71], v193 offset:40960
	ds_read_b128 v[234:237], v198 offset:32768
	ds_read_b128 v[238:241], v198 offset:40960
	v_exp_f32_e32 v216, v227
	v_exp_f32_e32 v227, v229
	s_waitcnt lgkmcnt(3)
	v_mfma_f32_32x32x16_bf16 v[80:95], v[64:67], v[112:115], 0
	v_exp_f32_e32 v229, v231
	v_exp_f32_e32 v231, v232
	v_exp_f32_e32 v232, v233
	v_exp_f32_e32 v233, v206
	v_add_f32_e32 v206, 0, v160
	v_add_f32_e32 v206, v175, v206
	v_add_f32_e32 v206, v161, v206
	s_waitcnt lgkmcnt(2)
	v_mfma_f32_32x32x16_bf16 v[64:79], v[68:71], v[112:115], 0
	v_add_f32_e32 v206, v174, v206
	v_add_f32_e32 v206, v162, v206
	v_add_f32_e32 v206, v173, v206
	v_add_f32_e32 v206, v163, v206
	v_add_f32_e32 v206, v172, v206
	v_add_f32_e32 v206, v164, v206
	v_add_f32_e32 v206, v171, v206
	s_waitcnt lgkmcnt(1)
	v_mfma_f32_32x32x16_bf16 v[80:95], v[234:237], v[108:111], v[80:95]
	v_add_f32_e32 v206, v165, v206
	v_add_f32_e32 v206, v170, v206
	v_add_f32_e32 v206, v166, v206
	v_exp_f32_e32 v217, v228
	v_add_f32_e32 v206, v169, v206
	v_add_f32_e32 v206, v167, v206
	v_exp_f32_e32 v228, v230
	s_waitcnt lgkmcnt(0)
	v_mfma_f32_32x32x16_bf16 v[64:79], v[238:241], v[108:111], v[64:79]
	ds_read_b128 v[234:237], v197 offset:32768
	ds_read_b128 v[238:241], v197 offset:40960
	v_add_f32_e32 v206, v168, v206
	v_add_f32_e32 v206, v216, v206
	v_exp_f32_e32 v214, v214
	v_add_f32_e32 v206, v217, v206
	v_exp_f32_e32 v215, v215
	v_add_f32_e32 v206, v227, v206
	s_waitcnt lgkmcnt(1)
	v_mfma_f32_32x32x16_bf16 v[80:95], v[234:237], v[120:123], v[80:95]
	v_exp_f32_e32 v222, v222
	v_add_f32_e32 v206, v228, v206
	v_exp_f32_e32 v223, v223
	v_add_f32_e32 v206, v229, v206
	v_exp_f32_e32 v224, v224
	v_add_f32_e32 v206, v214, v206
	v_exp_f32_e32 v225, v225
	s_waitcnt lgkmcnt(0)
	v_mfma_f32_32x32x16_bf16 v[64:79], v[238:241], v[120:123], v[64:79]
	ds_read_b128 v[234:237], v196 offset:32768
	ds_read_b128 v[238:241], v196 offset:40960
	v_add_f32_e32 v206, v215, v206
	v_exp_f32_e32 v226, v226
	v_add_f32_e32 v206, v222, v206
	v_exp_f32_e32 v230, v207
	v_add_f32_e32 v206, v223, v206
	v_add_f32_e32 v206, v224, v206
	s_waitcnt lgkmcnt(1)
; #define SBAR() __builtin_amdgcn_sched_barrier(0)
; __device__ __forceinline__ void finishSM(f32x16& p0, f32x16& p1, float alpha, float& l_reg, bf16x8& pa0, bf16x8& pa1, bf16x8& pa2, bf16x8& pa3) {
;   for (int r = 0; r < 16; ++r) p1[r] = __builtin_amdgcn_exp2f(p1[r]);
;   float ps = 0; for (int r = 0; r < 16; ++r) ps += p0[r]; for (int r = 0; r < 16; ++r) ps += p1[r];
;   { auto rr = __builtin_amdgcn_permlane32_swap(__float_as_uint(ps), __float_as_uint(ps), false, false);
;     ps = __uint_as_float(rr[0]) + __uint_as_float(rr[1]); }
;   l_reg = l_reg * alpha + ps;
;     ...
;   PK4(p0, 0, pa0); PK4(p0, 8, pa1); PK4(p1, 0, pa2); PK4(p1, 8, pa3);
;     ...
; }
; __device__ __forceinline__ void qkt(f32x16& p0, f32x16& p1, const bf16* Ks, const bf16x8* qr, int r32, int hi) {
;   p0 = f32x16{}; p1 = f32x16{};
;   for (int d0 = 0; d0 < 8; ++d0) { int cb = (d0 * 16 + hi * 8) * 2;
;     bf16x8 b0 = *reinterpret_cast<const bf16x8*>((const char*)Ks + KSWZ(r32, cb));
;     bf16x8 b1 = *reinterpret_cast<const bf16x8*>((const char*)Ks + KSWZ(32 + r32, cb));
;     p0 = __builtin_amdgcn_mfma_f32_32x32x16_bf16(b0, qr[d0], p0, 0, 0, 0);
;     p1 = __builtin_amdgcn_mfma_f32_32x32x16_bf16(b1, qr[d0], p1, 0, 0, 0); }
; }
; __device__ __forceinline__ int v_st(int k, int c) { const int kk = (k & ~0xC) | ((k & 4) << 1) | ((k & 8) >> 1); return ((kk >> 3) * 4 + (c >> 5)) * 512 + ((kk & 7) * 32 + (c & 31)) * 2; }
; __device__ __forceinline__ int v_rd_base(int lane) { return ((lane & 3) << 3) | (((lane >> 2) & 3) << 6) | (((lane >> 4) & 1) << 5) | (((lane >> 5) & 1) << 8); }
; template <int OFF> __device__ __forceinline__ s16x4 tr_read(int vb) {
;   s16x4 r; asm volatile("ds_read_b64_tr_b16 %0, %1 offset:%2" : "=&v"(r) : "v"(vb), "i"(OFF) : "memory"); return r;
; }
; template <typename TQ>
; __device__ __forceinline__ void attn_dense_body(const TQ* __restrict__ Qb, const bf16* __restrict__ Kh, const bf16* __restrict__ Vh,
;                                                 unsigned short* __restrict__ Ob, int seq, char* lds) {
;     ...
;     SBAR(); qkt(pA0, pA1, K_lds, qr, r32, hi);
;     finishSM(pB0, pB1, alB, l_reg, pa0, pa1, pa2, pa3); SBAR();
;     if (SDEPTH == 1 || j + 3 < NT) SLOAD(SE, (j + 1 + SDEPTH) * KVBLK); SBAR();
;     pv_d0(o, vb0 + (int)SHM_V, pa0, pa1, pa2, pa3); partialSM(pA0, pA1, m_reg, mnA, alA);
;     __syncthreads(); SWAIT(); SWRITE(1, SO);
	v_mfma_f32_32x32x16_bf16 v[80:95], v[234:237], v[124:127], v[80:95]
	v_add_f32_e32 v206, v225, v206
	v_add_f32_e32 v206, v226, v206
	v_add_f32_e32 v206, v230, v206
	v_add_f32_e32 v206, v231, v206
	v_add_f32_e32 v206, v232, v206
	v_add_f32_e32 v206, v233, v206
	v_mov_b32_e32 v207, v206
	s_waitcnt lgkmcnt(0)
	v_mfma_f32_32x32x16_bf16 v[64:79], v[238:241], v[124:127], v[64:79]
	ds_read_b128 v[234:237], v194 offset:32768
	ds_read_b128 v[238:241], v194 offset:40960
	v_permlane32_swap_b32_e32 v206, v207
	s_waitcnt lgkmcnt(1)
	v_mfma_f32_32x32x16_bf16 v[80:95], v[234:237], v[116:119], v[80:95]
	s_waitcnt lgkmcnt(0)
	v_mfma_f32_32x32x16_bf16 v[64:79], v[238:241], v[116:119], v[64:79]
	ds_read_b128 v[234:237], v195 offset:32768
	ds_read_b128 v[238:241], v195 offset:40960
	s_waitcnt lgkmcnt(1)
	v_mfma_f32_32x32x16_bf16 v[80:95], v[234:237], v[104:107], v[80:95]
	s_waitcnt lgkmcnt(0)
	v_mfma_f32_32x32x16_bf16 v[64:79], v[238:241], v[104:107], v[64:79]
	ds_read_b128 v[234:237], v200 offset:32768
	ds_read_b128 v[238:241], v200 offset:40960
	s_waitcnt lgkmcnt(1)
	v_mfma_f32_32x32x16_bf16 v[80:95], v[234:237], v[100:103], v[80:95]
	s_waitcnt lgkmcnt(0)
	v_mfma_f32_32x32x16_bf16 v[64:79], v[238:241], v[100:103], v[64:79]
	ds_read_b128 v[234:237], v199 offset:32768
	ds_read_b128 v[238:241], v199 offset:40960
	v_cvt_pk_bf16_f32 v160, v160, v175
	v_cvt_pk_bf16_f32 v161, v161, v174
	v_cvt_pk_bf16_f32 v162, v162, v173
	v_cvt_pk_bf16_f32 v163, v163, v172
	v_cvt_pk_bf16_f32 v164, v164, v171
	v_cvt_pk_bf16_f32 v165, v165, v170
	s_waitcnt lgkmcnt(1)
	v_mfma_f32_32x32x16_bf16 v[80:95], v[234:237], v[96:99], v[80:95]
	v_cvt_pk_bf16_f32 v166, v166, v169
	v_cvt_pk_bf16_f32 v167, v167, v168
	v_cvt_pk_bf16_f32 v168, v216, v217
	v_cvt_pk_bf16_f32 v169, v227, v228
	v_cvt_pk_bf16_f32 v170, v229, v214
	v_cvt_pk_bf16_f32 v171, v215, v222
	v_cvt_pk_bf16_f32 v172, v223, v224
	s_waitcnt lgkmcnt(0)
	v_mfma_f32_32x32x16_bf16 v[64:79], v[238:241], v[96:99], v[64:79]
	v_cvt_pk_bf16_f32 v173, v225, v226
	v_cvt_pk_bf16_f32 v174, v230, v231
	v_cvt_pk_bf16_f32 v175, v232, v233
	v_permlane32_swap_b32_e32 v160, v162
	v_permlane32_swap_b32_e32 v161, v163
	v_permlane32_swap_b32_e32 v164, v166
	v_permlane32_swap_b32_e32 v165, v167
	v_permlane32_swap_b32_e32 v168, v170
	v_permlane32_swap_b32_e32 v169, v171
	v_permlane32_swap_b32_e32 v172, v174
	v_permlane32_swap_b32_e32 v173, v175
	s_cmp_ge_u32 s2, s27
	s_cselect_b64 s[42:43], -1, 0
	s_and_b64 vcc, exec, s[42:43]
	s_cbranch_vccnz .LBB0_82
.LBB0_82:
	ds_read_b64_tr_b16 v[222:223], v187 offset:0
	ds_read_b64_tr_b16 v[224:225], v187 offset:0x800
	ds_read_b64_tr_b16 v[226:227], v187 offset:0x1000
	ds_read_b64_tr_b16 v[228:229], v187 offset:0x1800
	ds_read_b64_tr_b16 v[230:231], v187 offset:0x2000
	ds_read_b64_tr_b16 v[232:233], v187 offset:0x2800
	ds_read_b64_tr_b16 v[234:235], v187 offset:0x3000
	ds_read_b64_tr_b16 v[236:237], v187 offset:0x3800
	s_waitcnt lgkmcnt(0)
	s_nop 0
	v_mfma_f32_32x32x16_bf16 v[0:15], v[160:163], v[222:225], v[0:15]
	ds_read_b64_tr_b16 v[222:223], v187 offset:0x200
	ds_read_b64_tr_b16 v[224:225], v187 offset:0xa00
	v_mfma_f32_32x32x16_bf16 v[0:15], v[164:167], v[226:229], v[0:15]
	ds_read_b64_tr_b16 v[226:227], v187 offset:0x1200
	ds_read_b64_tr_b16 v[228:229], v187 offset:0x1a00
	v_mfma_f32_32x32x16_bf16 v[0:15], v[168:171], v[230:233], v[0:15]
	ds_read_b64_tr_b16 v[230:231], v187 offset:0x2200
	ds_read_b64_tr_b16 v[232:233], v187 offset:0x2a00
	v_mfma_f32_32x32x16_bf16 v[0:15], v[172:175], v[234:237], v[0:15]
	ds_read_b64_tr_b16 v[234:235], v187 offset:0x3200
	ds_read_b64_tr_b16 v[236:237], v187 offset:0x3a00
	s_waitcnt lgkmcnt(0)
	v_mfma_f32_32x32x16_bf16 v[48:63], v[160:163], v[222:225], v[48:63]
	ds_read_b64_tr_b16 v[222:223], v187 offset:0x400
	ds_read_b64_tr_b16 v[224:225], v187 offset:0xc00
	v_mfma_f32_32x32x16_bf16 v[48:63], v[164:167], v[226:229], v[48:63]
	ds_read_b64_tr_b16 v[226:227], v187 offset:0x1400
	ds_read_b64_tr_b16 v[228:229], v187 offset:0x1c00
	v_mfma_f32_32x32x16_bf16 v[48:63], v[168:171], v[230:233], v[48:63]
	ds_read_b64_tr_b16 v[230:231], v187 offset:0x2400
	ds_read_b64_tr_b16 v[232:233], v187 offset:0x2c00
	v_mfma_f32_32x32x16_bf16 v[48:63], v[172:175], v[234:237], v[48:63]
	ds_read_b64_tr_b16 v[234:235], v187 offset:0x3400
	ds_read_b64_tr_b16 v[236:237], v187 offset:0x3c00
	s_waitcnt lgkmcnt(0)
	v_mfma_f32_32x32x16_bf16 v[32:47], v[160:163], v[222:225], v[32:47]
	ds_read_b64_tr_b16 v[222:223], v187 offset:0x600
	ds_read_b64_tr_b16 v[224:225], v187 offset:0xe00
	v_mfma_f32_32x32x16_bf16 v[32:47], v[164:167], v[226:229], v[32:47]
	ds_read_b64_tr_b16 v[226:227], v187 offset:0x1600
	ds_read_b64_tr_b16 v[228:229], v187 offset:0x1e00
	v_mfma_f32_32x32x16_bf16 v[32:47], v[168:171], v[230:233], v[32:47]
	ds_read_b64_tr_b16 v[230:231], v187 offset:0x2600
	ds_read_b64_tr_b16 v[232:233], v187 offset:0x2e00
	v_mfma_f32_32x32x16_bf16 v[32:47], v[172:175], v[234:237], v[32:47]
	ds_read_b64_tr_b16 v[234:235], v187 offset:0x3600
	ds_read_b64_tr_b16 v[236:237], v187 offset:0x3e00
	s_waitcnt lgkmcnt(0)
	v_mfma_f32_32x32x16_bf16 v[16:31], v[160:163], v[222:225], v[16:31]
	v_max_f32_e32 v160, v81, v81
	v_max_f32_e32 v161, v80, v80
	v_max_f32_e32 v160, v161, v160
	v_max3_f32 v160, v160, v82, v83
	v_max3_f32 v160, v160, v84, v85
	v_max3_f32 v160, v160, v86, v87
	v_max3_f32 v160, v160, v88, v89
	v_max3_f32 v160, v160, v90, v91
	v_max3_f32 v160, v160, v92, v93
	v_mfma_f32_32x32x16_bf16 v[16:31], v[164:167], v[226:229], v[16:31]
	v_max3_f32 v160, v160, v94, v95
	v_max3_f32 v160, v160, v64, v65
	v_max3_f32 v160, v160, v66, v67
	v_max3_f32 v160, v160, v68, v69
	v_max3_f32 v160, v160, v70, v71
	v_max3_f32 v160, v160, v72, v73
	v_max3_f32 v160, v160, v74, v75
	v_max3_f32 v160, v160, v76, v77
	v_mfma_f32_32x32x16_bf16 v[16:31], v[168:171], v[230:233], v[16:31]
	v_max3_f32 v160, v160, v78, v79
	v_mov_b32_e32 v161, v160
	s_nop 1
	v_permlane32_swap_b32_e32 v160, v161
	v_max_f32_e32 v161, v161, v161
	v_max_f32_e32 v160, v160, v160
	v_max_f32_e32 v160, v160, v161
	v_sub_f32_e32 v161, v160, v205
	v_cmp_ge_f32_e32 vcc, s4, v161
	v_max_f32_e32 v161, v205, v205
	v_max_f32_e32 v161, v161, v160
	v_mfma_f32_32x32x16_bf16 v[16:31], v[172:175], v[234:237], v[16:31]
	v_sub_f32_e32 v160, v205, v161
	v_mul_f32_e32 v160, 0x3e0293ee, v160
	v_exp_f32_e32 v160, v160
	s_cmp_eq_u64 vcc, exec
	s_cselect_b64 s[0:1], -1, 0
	s_waitcnt vmcnt(0)
	s_barrier
; #define SBAR() __builtin_amdgcn_sched_barrier(0)
; #define SWAIT() do { if constexpr (SDEPTH == 2) asm volatile("s_waitcnt vmcnt(4)" ::: "memory"); else asm volatile("s_waitcnt vmcnt(0)" ::: "memory"); } while (0)
; #define RESC(a) do { if (__any((a) < 1.f)) { if (hi == 0) al_l[r32] = (a); asm volatile("s_waitcnt lgkmcnt(0)" ::: "memory"); \
;     for (int d = 0; d < 4; ++d) for (int r = 0; r < 16; ++r) o[d][r] *= al_l[crow(r, hi)]; } } while (0)
; template <typename TQ>
; __device__ __forceinline__ void attn_dense_body(const TQ* __restrict__ Qb, const bf16* __restrict__ Kh, const bf16* __restrict__ Vh,
;                                                 unsigned short* __restrict__ Ob, int seq, char* lds) {
;     ...
;     pv_d0(o, vb0 + (int)SHM_V, pa0, pa1, pa2, pa3); partialSM(pA0, pA1, m_reg, mnA, alA);
;     __syncthreads(); SWAIT(); SWRITE(1, SO);
;     RESC(alA); __syncthreads();
;   }
;   SBAR(); qkt(pB0, pB1, (bf16*)((char*)K_lds + SHM_K), qr, r32, hi);
;   finishSM(pA0, pA1, alA, l_reg, pa0, pa1, pa2, pa3); SBAR();
	v_cndmask_b32_e64 v160, v160, 1.0, s[0:1]
	v_cmp_gt_f32_e32 vcc, 1.0, v160
	s_add_i32 m0, s5, s28
	s_add_i32 m0, m0, 0xc000
	s_nop 0
	global_load_lds_dwordx4 v128, s[6:7]
	s_add_i32 m0, s5, s28
	s_add_i32 m0, m0, 0xc400
	s_nop 0
	global_load_lds_dwordx4 v129, s[6:7]
	s_add_i32 m0, s5, s28
	s_add_i32 m0, m0, 0x0
	s_nop 0
	global_load_lds_dwordx4 v130, s[68:69]
	s_add_i32 m0, s5, s28
	s_add_i32 m0, m0, 0x400
	s_nop 0
	global_load_lds_dwordx4 v131, s[68:69]
	s_add_u32 s6, s6, 0x4000
	s_addc_u32 s7, s7, 0
	s_add_u32 s68, s68, 0x4000
	s_addc_u32 s69, s69, 0
	v_xor_b32_e32 v187, 0x10000, v187
	v_xor_b32_e32 v188, 0x10000, v188
	s_xor_b32 s28, s28, 0x10000
	s_xor_b32 s29, s29, 0x10000
	s_cbranch_vccz .LBB0_86
	s_and_saveexec_b64 s[46:47], s[38:39]
	ds_write_b32 v185, v160 offset:128
	s_or_b64 exec, exec, s[46:47]
	s_waitcnt lgkmcnt(0)
	v_add_u32_e32 v156, v184, v208
	ds_read_b128 v[144:147], v156 offset:224
	ds_read_b128 v[148:151], v156 offset:192
	ds_read_b128 v[152:155], v156 offset:160
	ds_read_b128 v[156:159], v156 offset:128
	s_waitcnt lgkmcnt(3)
	v_pk_mul_f32 v[12:13], v[12:13], v[144:145]
	s_waitcnt lgkmcnt(2)
	v_pk_mul_f32 v[8:9], v[8:9], v[148:149]
	s_waitcnt lgkmcnt(1)
	v_pk_mul_f32 v[4:5], v[4:5], v[152:153]
	v_pk_mul_f32 v[14:15], v[14:15], v[146:147]
	v_pk_mul_f32 v[10:11], v[10:11], v[150:151]
	v_pk_mul_f32 v[6:7], v[6:7], v[154:155]
	s_waitcnt lgkmcnt(0)
	v_pk_mul_f32 v[2:3], v[2:3], v[158:159]
	v_pk_mul_f32 v[0:1], v[0:1], v[156:157]
	v_pk_mul_f32 v[60:61], v[60:61], v[144:145]
	v_pk_mul_f32 v[56:57], v[56:57], v[148:149]
	v_pk_mul_f32 v[52:53], v[52:53], v[152:153]
	v_pk_mul_f32 v[62:63], v[62:63], v[146:147]
	v_pk_mul_f32 v[58:59], v[58:59], v[150:151]
	v_pk_mul_f32 v[54:55], v[54:55], v[154:155]
	v_pk_mul_f32 v[50:51], v[50:51], v[158:159]
	v_pk_mul_f32 v[48:49], v[48:49], v[156:157]
	v_pk_mul_f32 v[44:45], v[44:45], v[144:145]
	v_pk_mul_f32 v[40:41], v[40:41], v[148:149]
	v_pk_mul_f32 v[36:37], v[36:37], v[152:153]
	v_pk_mul_f32 v[46:47], v[46:47], v[146:147]
	v_pk_mul_f32 v[42:43], v[42:43], v[150:151]
	v_pk_mul_f32 v[38:39], v[38:39], v[154:155]
	v_pk_mul_f32 v[34:35], v[34:35], v[158:159]
	v_pk_mul_f32 v[32:33], v[32:33], v[156:157]
	v_pk_mul_f32 v[28:29], v[28:29], v[144:145]
	v_pk_mul_f32 v[24:25], v[24:25], v[148:149]
	v_pk_mul_f32 v[20:21], v[20:21], v[152:153]
	v_pk_mul_f32 v[30:31], v[30:31], v[146:147]
	v_pk_mul_f32 v[26:27], v[26:27], v[150:151]
	v_pk_mul_f32 v[22:23], v[22:23], v[154:155]
	v_pk_mul_f32 v[18:19], v[18:19], v[158:159]
	v_pk_mul_f32 v[16:17], v[16:17], v[156:157]
.LBB0_86:
	v_cndmask_b32_e64 v168, v161, v205, s[0:1]
	v_mul_f32_e32 v144, 0xbe0293ee, v168
	v_mov_b32_e32 v145, v144
	v_fmamk_f32 v80, v80, 0x3e0293ee, v144
	v_fmamk_f32 v81, v81, 0x3e0293ee, v144
	v_fmamk_f32 v82, v82, 0x3e0293ee, v144
	v_fmamk_f32 v83, v83, 0x3e0293ee, v144
	v_fmamk_f32 v84, v84, 0x3e0293ee, v144
	v_fmamk_f32 v85, v85, 0x3e0293ee, v144
	v_fmamk_f32 v86, v86, 0x3e0293ee, v144
	v_fmamk_f32 v87, v87, 0x3e0293ee, v144
	v_fmamk_f32 v88, v88, 0x3e0293ee, v144
	v_fmamk_f32 v89, v89, 0x3e0293ee, v144
	v_fmamk_f32 v90, v90, 0x3e0293ee, v144
	v_fmamk_f32 v91, v91, 0x3e0293ee, v144
	v_fmamk_f32 v92, v92, 0x3e0293ee, v144
	v_fmamk_f32 v93, v93, 0x3e0293ee, v144
	v_fmamk_f32 v94, v94, 0x3e0293ee, v144
	v_fmac_f32_e32 v145, 0x3e0293ee, v95
	v_exp_f32_e32 v161, v80
	v_exp_f32_e32 v175, v81
	v_exp_f32_e32 v162, v82
	v_exp_f32_e32 v205, v83
	v_exp_f32_e32 v174, v84
	v_exp_f32_e32 v214, v85
	v_exp_f32_e32 v163, v86
	v_exp_f32_e32 v173, v87
	v_exp_f32_e32 v164, v88
	v_exp_f32_e32 v171, v89
	v_exp_f32_e32 v165, v90
	v_exp_f32_e32 v172, v91
	v_exp_f32_e32 v166, v92
	v_exp_f32_e32 v169, v93
	v_exp_f32_e32 v167, v94
	v_exp_f32_e32 v170, v145
	v_pk_fma_f32 v[158:159], v[64:65], s[22:23], v[144:145] op_sel_hi:[1,0,0]
	v_add_f32_e32 v64, v202, v203
	v_fmac_f32_e32 v64, v201, v186
	v_add_f32_e32 v186, v206, v207
	s_mov_b64 s[0:1], 0x8000
	v_pk_fma_f32 v[156:157], v[66:67], s[22:23], v[144:145] op_sel_hi:[1,0,0]
	v_pk_fma_f32 v[152:153], v[68:69], s[22:23], v[144:145] op_sel_hi:[1,0,0]
	v_pk_fma_f32 v[148:149], v[70:71], s[22:23], v[144:145] op_sel_hi:[1,0,0]
	v_pk_fma_f32 v[146:147], v[72:73], s[22:23], v[144:145] op_sel_hi:[1,0,0]
	v_pk_fma_f32 v[154:155], v[74:75], s[22:23], v[144:145] op_sel_hi:[1,0,0]
	v_pk_fma_f32 v[150:151], v[76:77], s[22:23], v[144:145] op_sel_hi:[1,0,0]
	v_pk_fma_f32 v[144:145], v[78:79], s[22:23], v[144:145] op_sel_hi:[1,0,0]
	v_fmac_f32_e32 v186, v64, v204
	s_add_i32 s2, s2, 2
	v_lshl_add_u64 v[180:181], v[180:181], 0, s[0:1]
	s_and_b64 vcc, exec, s[42:43]
	s_waitcnt lgkmcnt(0)
	s_cbranch_vccnz .LBB0_88
	v_mov_b32_e32 v201, v160
	s_branch .LBB0_76
